# scan consumer: packed f32 for the element-wise parts; MLP relu2 epilogue: canonicalising v_max dropped (wide-store WAR padded)
# speedup vs baseline: 1.0042x; 1.0042x over previous
; #define LAS __attribute__((address_space(3)))
; __device__ __forceinline__ float sum16(float x) { x += dpp_f<0xB1>(x); x += dpp_f<0x4E>(x); x += dpp_f<0x141>(x); x += dpp_f<0x140>(x); return x; }
; __device__ __forceinline__ void rwkv_scan_phase(LAS unsigned char* lds, const bf16_t* RKV, const float* DEC, const float* AF, const float* k_k, const float* k_a, const float* r_k, float* BON, float* Y, int bx, const int tid) {
;     ...
;     for (int c = 0; c < SEQ / SC_T; ++c) {
;         if (wid >= 4) { if (c + 1 < SEQ / SC_T) { SCAN_STORE((c + 1) & 1, c + 1); if (c + 2 < SEQ / SC_T) SCAN_LOAD(c + 2); } }
;         else {
;             const LAS unsigned char* base = lds + (c & 1) * SC_BUF + ks4; const LAS unsigned char* vbase = lds + (c & 1) * SC_BUF + 768 + rowi * 4;
;             f32x4 r4 = *(const LAS f32x4*)(base), w4 = *(const LAS f32x4*)(base + 256), k4 = *(const LAS f32x4*)(base + 512), a4 = *(const LAS f32x4*)(base + 1024), b4 = *(const LAS f32x4*)(base + 1280);
;             float vv = *(const LAS float*)(vbase); float ykeep = 0.f;
; #pragma unroll
;             for (int t = 0; t < SC_T; ++t) {
;                 f32x4 r4n = r4, w4n = w4, k4n = k4, a4n = a4, b4n = b4; float vvn = vv;
;                 if (t + 1 < SC_T) { const LAS unsigned char* p = base + (t + 1) * SC_TOK;
;                     r4n = *(const LAS f32x4*)(p); w4n = *(const LAS f32x4*)(p + 256); k4n = *(const LAS f32x4*)(p + 512); a4n = *(const LAS f32x4*)(p + 1024); b4n = *(const LAS f32x4*)(p + 1280);
;                     vvn = *(const LAS float*)(vbase + (t + 1) * SC_TOK); }
;                 const f32x2 a01 = {a4[0], a4[1]}, a23 = {a4[2], a4[3]}, w01 = {w4[0], w4[1]}, w23 = {w4[2], w4[3]}, b01 = {b4[0], b4[1]}, b23 = {b4[2], b4[3]}, k01 = {k4[0], k4[1]}, k23 = {k4[2], k4[3]}, r01 = {r4[0], r4[1]}, r23 = {r4[2], r4[3]};
;                 const f32x2 tsa = S01 * a01 + S23 * a23; const float sa = sum16(tsa[0] + tsa[1]);
;                 S01 = S01 * w01 + (b01 * sa + k01 * vv); S23 = S23 * w23 + (b23 * sa + k23 * vv);
;                 const f32x2 ty = S01 * r01 + S23 * r23; const float y = sum16(ty[0] + ty[1]);
;                 ykeep = ((lane & 15) == (t & 15)) ? y : ykeep;
;                 if ((t & 15) == 15) yp[(size_t)(c * SC_T + (t - 15) + (lane & 15)) * 2048] = ykeep;
;                 r4 = r4n; w4 = w4n; k4 = k4n; a4 = a4n; b4 = b4n; vv = vvn;
.LBB0_224:
	v_readlane_b32 s52, v255, 42
	v_readlane_b32 s53, v255, 43
	s_add_i32 s35, s21, -1
	s_mov_b64 s[76:77], -1
	s_and_b64 vcc, exec, s[52:53]
	s_cbranch_vccz .LBB0_226
	s_bitcmp1_b32 s35, 0
	s_cselect_b32 s52, 0xc000, 0
	v_add_u32_e32 v50, s52, v106
	v_add_u32_e32 v51, s52, v107
	ds_read_b128 v[0:3], v50 offset:1024
	ds_read_b128 v[8:11], v50 offset:512
	ds_read2st64_b32 v[40:41], v51 offset0:3 offset1:9
	ds_read_b128 v[4:7], v50 offset:256
	ds_read_b128 v[12:15], v50 offset:1280
	ds_read_b128 v[16:19], v50
	ds_read_b128 v[20:23], v50 offset:2560
	s_mov_b32 s40, 0xaaaaaaaa
	s_mov_b32 s41, 0xaaaaaaaa
	s_mov_b32 s46, 0xcccccccc
	s_mov_b32 s47, 0xcccccccc
	s_mov_b64 s[76:77], 0x20000
	s_waitcnt lgkmcnt(0)
	v_mul_f32_e32 v48, v94, v0
	v_fmac_f32_e32 v48, v95, v1
	v_fmac_f32_e32 v48, v96, v2
	v_fmac_f32_e32 v48, v97, v3
	ds_read_b128 v[0:3], v50 offset:4096
	ds_read_b128 v[28:31], v50 offset:2048
	ds_read_b128 v[24:27], v50 offset:1792
	v_add_f32_dpp v48, v48, v48 quad_perm:[1,0,3,2] row_mask:0xf bank_mask:0xf bound_ctrl:1
	v_pk_mul_f32 v[44:45], v[8:9], v[40:41] op_sel_hi:[1,0]
	v_pk_mul_f32 v[46:47], v[10:11], v[40:41] op_sel_hi:[1,0]
	v_add_f32_dpp v48, v48, v48 quad_perm:[2,3,0,1] row_mask:0xf bank_mask:0xf bound_ctrl:1
	v_pk_fma_f32 v[44:45], v[94:95], v[4:5], v[44:45]
	v_pk_fma_f32 v[46:47], v[96:97], v[6:7], v[46:47]
	v_add_f32_dpp v48, v48, v48 row_half_mirror row_mask:0xf bank_mask:0xf bound_ctrl:1
	ds_read_b128 v[32:35], v50 offset:2816
	ds_read_b128 v[36:39], v50 offset:1536
	v_add_f32_dpp v48, v48, v48 row_mirror row_mask:0xf bank_mask:0xf bound_ctrl:1
	v_pk_fma_f32 v[44:45], v[12:13], v[48:49], v[44:45] op_sel_hi:[1,0,1]
	v_pk_fma_f32 v[46:47], v[14:15], v[48:49], v[46:47] op_sel_hi:[1,0,1]
	v_pk_mul_f32 v[48:49], v[44:45], v[20:21]
	v_pk_mul_f32 v[76:77], v[44:45], v[16:17]
	v_pk_fma_f32 v[48:49], v[46:47], v[22:23], v[48:49]
	v_pk_fma_f32 v[76:77], v[46:47], v[18:19], v[76:77]
	v_add_f32_e32 v48, v48, v49
	v_add_f32_e32 v60, v76, v77
	ds_read_b128 v[20:23], v50 offset:5632
	ds_read_b128 v[8:11], v50 offset:3584
	ds_read2st64_b32 v[42:43], v51 offset0:15 offset1:21
	ds_read_b128 v[4:7], v50 offset:3328
	s_waitcnt lgkmcnt(4)
	v_add_f32_dpp v48, v48, v48 quad_perm:[1,0,3,2] row_mask:0xf bank_mask:0xf bound_ctrl:1
	v_pk_mul_f32 v[94:95], v[28:29], v[40:41] op_sel:[0,1]
	v_pk_mul_f32 v[96:97], v[30:31], v[40:41] op_sel:[0,1]
	v_add_f32_dpp v48, v48, v48 quad_perm:[2,3,0,1] row_mask:0xf bank_mask:0xf bound_ctrl:1
	v_pk_fma_f32 v[94:95], v[44:45], v[24:25], v[94:95]
	v_pk_fma_f32 v[96:97], v[46:47], v[26:27], v[96:97]
	v_add_f32_dpp v48, v48, v48 row_half_mirror row_mask:0xf bank_mask:0xf bound_ctrl:1
	ds_read_b128 v[12:15], v50 offset:4352
	ds_read_b128 v[16:19], v50 offset:3072
	v_add_f32_dpp v48, v48, v48 row_mirror row_mask:0xf bank_mask:0xf bound_ctrl:1
	v_pk_fma_f32 v[94:95], v[32:33], v[48:49], v[94:95] op_sel_hi:[1,0,1]
	v_pk_fma_f32 v[96:97], v[34:35], v[48:49], v[96:97] op_sel_hi:[1,0,1]
	v_pk_mul_f32 v[48:49], v[94:95], v[0:1]
	v_pk_mul_f32 v[76:77], v[94:95], v[36:37]
	v_pk_fma_f32 v[48:49], v[96:97], v[2:3], v[48:49]
	v_pk_fma_f32 v[76:77], v[96:97], v[38:39], v[76:77]
	v_add_f32_e32 v48, v48, v49
	v_add_f32_e32 v61, v76, v77
	ds_read_b128 v[0:3], v50 offset:7168
	ds_read_b128 v[28:31], v50 offset:5120
	ds_read_b128 v[24:27], v50 offset:4864
	s_waitcnt lgkmcnt(3)
	v_add_f32_dpp v48, v48, v48 quad_perm:[1,0,3,2] row_mask:0xf bank_mask:0xf bound_ctrl:1
	v_pk_mul_f32 v[44:45], v[8:9], v[42:43] op_sel_hi:[1,0]
	v_pk_mul_f32 v[46:47], v[10:11], v[42:43] op_sel_hi:[1,0]
	v_add_f32_dpp v48, v48, v48 quad_perm:[2,3,0,1] row_mask:0xf bank_mask:0xf bound_ctrl:1
	v_pk_fma_f32 v[44:45], v[94:95], v[4:5], v[44:45]
	v_pk_fma_f32 v[46:47], v[96:97], v[6:7], v[46:47]
	v_add_f32_dpp v48, v48, v48 row_half_mirror row_mask:0xf bank_mask:0xf bound_ctrl:1
	ds_read_b128 v[32:35], v50 offset:5888
	ds_read_b128 v[36:39], v50 offset:4608
	v_add_f32_dpp v48, v48, v48 row_mirror row_mask:0xf bank_mask:0xf bound_ctrl:1
	v_pk_fma_f32 v[44:45], v[12:13], v[48:49], v[44:45] op_sel_hi:[1,0,1]
	v_pk_fma_f32 v[46:47], v[14:15], v[48:49], v[46:47] op_sel_hi:[1,0,1]
	v_pk_mul_f32 v[48:49], v[44:45], v[20:21]
	v_pk_mul_f32 v[76:77], v[44:45], v[16:17]
	v_pk_fma_f32 v[48:49], v[46:47], v[22:23], v[48:49]
	v_pk_fma_f32 v[76:77], v[46:47], v[18:19], v[76:77]
	v_add_f32_e32 v48, v48, v49
	v_add_f32_e32 v62, v76, v77
	ds_read_b128 v[20:23], v50 offset:8704
	ds_read_b128 v[8:11], v50 offset:6656
	ds_read2st64_b32 v[40:41], v51 offset0:27 offset1:33
	ds_read_b128 v[4:7], v50 offset:6400
	s_waitcnt lgkmcnt(4)
	v_add_f32_dpp v48, v48, v48 quad_perm:[1,0,3,2] row_mask:0xf bank_mask:0xf bound_ctrl:1
	v_pk_mul_f32 v[94:95], v[28:29], v[42:43] op_sel:[0,1]
	v_pk_mul_f32 v[96:97], v[30:31], v[42:43] op_sel:[0,1]
	v_add_f32_dpp v48, v48, v48 quad_perm:[2,3,0,1] row_mask:0xf bank_mask:0xf bound_ctrl:1
	v_pk_fma_f32 v[94:95], v[44:45], v[24:25], v[94:95]
	v_pk_fma_f32 v[96:97], v[46:47], v[26:27], v[96:97]
	v_add_f32_dpp v48, v48, v48 row_half_mirror row_mask:0xf bank_mask:0xf bound_ctrl:1
	ds_read_b128 v[12:15], v50 offset:7424
	ds_read_b128 v[16:19], v50 offset:6144
	v_add_f32_dpp v48, v48, v48 row_mirror row_mask:0xf bank_mask:0xf bound_ctrl:1
	v_pk_fma_f32 v[94:95], v[32:33], v[48:49], v[94:95] op_sel_hi:[1,0,1]
	v_pk_fma_f32 v[96:97], v[34:35], v[48:49], v[96:97] op_sel_hi:[1,0,1]
	v_pk_mul_f32 v[48:49], v[94:95], v[0:1]
	v_pk_mul_f32 v[76:77], v[94:95], v[36:37]
	v_pk_fma_f32 v[48:49], v[96:97], v[2:3], v[48:49]
	v_pk_fma_f32 v[76:77], v[96:97], v[38:39], v[76:77]
	v_add_f32_e32 v48, v48, v49
	v_add_f32_e32 v63, v76, v77
	ds_read_b128 v[0:3], v50 offset:10240
	ds_read_b128 v[28:31], v50 offset:8192
	ds_read_b128 v[24:27], v50 offset:7936
	s_waitcnt lgkmcnt(3)
; #define LAS __attribute__((address_space(3)))
; __device__ __forceinline__ float sum16(float x) { x += dpp_f<0xB1>(x); x += dpp_f<0x4E>(x); x += dpp_f<0x141>(x); x += dpp_f<0x140>(x); return x; }
; __device__ __forceinline__ void rwkv_scan_phase(LAS unsigned char* lds, const bf16_t* RKV, const float* DEC, const float* AF, const float* k_k, const float* k_a, const float* r_k, float* BON, float* Y, int bx, const int tid) {
;     ...
;             for (int t = 0; t < SC_T; ++t) {
;                 f32x4 r4n = r4, w4n = w4, k4n = k4, a4n = a4, b4n = b4; float vvn = vv;
;                 if (t + 1 < SC_T) { const LAS unsigned char* p = base + (t + 1) * SC_TOK;
;                     r4n = *(const LAS f32x4*)(p); w4n = *(const LAS f32x4*)(p + 256); k4n = *(const LAS f32x4*)(p + 512); a4n = *(const LAS f32x4*)(p + 1024); b4n = *(const LAS f32x4*)(p + 1280);
;                     vvn = *(const LAS float*)(vbase + (t + 1) * SC_TOK); }
;                 const f32x2 a01 = {a4[0], a4[1]}, a23 = {a4[2], a4[3]}, w01 = {w4[0], w4[1]}, w23 = {w4[2], w4[3]}, b01 = {b4[0], b4[1]}, b23 = {b4[2], b4[3]}, k01 = {k4[0], k4[1]}, k23 = {k4[2], k4[3]}, r01 = {r4[0], r4[1]}, r23 = {r4[2], r4[3]};
;                 const f32x2 tsa = S01 * a01 + S23 * a23; const float sa = sum16(tsa[0] + tsa[1]);
;                 S01 = S01 * w01 + (b01 * sa + k01 * vv); S23 = S23 * w23 + (b23 * sa + k23 * vv);
;                 const f32x2 ty = S01 * r01 + S23 * r23; const float y = sum16(ty[0] + ty[1]);
;                 ykeep = ((lane & 15) == (t & 15)) ? y : ykeep;
;                 if ((t & 15) == 15) yp[(size_t)(c * SC_T + (t - 15) + (lane & 15)) * 2048] = ykeep;
;                 r4 = r4n; w4 = w4n; k4 = k4n; a4 = a4n; b4 = b4n; vv = vvn;
	v_add_f32_dpp v48, v48, v48 quad_perm:[1,0,3,2] row_mask:0xf bank_mask:0xf bound_ctrl:1
	v_pk_mul_f32 v[44:45], v[8:9], v[40:41] op_sel_hi:[1,0]
	v_pk_mul_f32 v[46:47], v[10:11], v[40:41] op_sel_hi:[1,0]
	v_add_f32_dpp v48, v48, v48 quad_perm:[2,3,0,1] row_mask:0xf bank_mask:0xf bound_ctrl:1
	v_pk_fma_f32 v[44:45], v[94:95], v[4:5], v[44:45]
	v_pk_fma_f32 v[46:47], v[96:97], v[6:7], v[46:47]
	v_add_f32_dpp v48, v48, v48 row_half_mirror row_mask:0xf bank_mask:0xf bound_ctrl:1
	ds_read_b128 v[32:35], v50 offset:8960
	ds_read_b128 v[36:39], v50 offset:7680
	v_add_f32_dpp v48, v48, v48 row_mirror row_mask:0xf bank_mask:0xf bound_ctrl:1
	v_pk_fma_f32 v[44:45], v[12:13], v[48:49], v[44:45] op_sel_hi:[1,0,1]
	v_pk_fma_f32 v[46:47], v[14:15], v[48:49], v[46:47] op_sel_hi:[1,0,1]
	v_pk_mul_f32 v[48:49], v[44:45], v[20:21]
	v_pk_mul_f32 v[76:77], v[44:45], v[16:17]
	v_pk_fma_f32 v[48:49], v[46:47], v[22:23], v[48:49]
	v_pk_fma_f32 v[76:77], v[46:47], v[18:19], v[76:77]
	v_add_f32_e32 v48, v48, v49
	v_add_f32_e32 v64, v76, v77
	ds_read_b128 v[20:23], v50 offset:11776
	ds_read_b128 v[8:11], v50 offset:9728
	ds_read2st64_b32 v[42:43], v51 offset0:39 offset1:45
	ds_read_b128 v[4:7], v50 offset:9472
	s_waitcnt lgkmcnt(4)
	v_add_f32_dpp v48, v48, v48 quad_perm:[1,0,3,2] row_mask:0xf bank_mask:0xf bound_ctrl:1
	v_pk_mul_f32 v[94:95], v[28:29], v[40:41] op_sel:[0,1]
	v_pk_mul_f32 v[96:97], v[30:31], v[40:41] op_sel:[0,1]
	v_add_f32_dpp v48, v48, v48 quad_perm:[2,3,0,1] row_mask:0xf bank_mask:0xf bound_ctrl:1
	v_pk_fma_f32 v[94:95], v[44:45], v[24:25], v[94:95]
	v_pk_fma_f32 v[96:97], v[46:47], v[26:27], v[96:97]
	v_add_f32_dpp v48, v48, v48 row_half_mirror row_mask:0xf bank_mask:0xf bound_ctrl:1
	ds_read_b128 v[12:15], v50 offset:10496
	ds_read_b128 v[16:19], v50 offset:9216
	v_add_f32_dpp v48, v48, v48 row_mirror row_mask:0xf bank_mask:0xf bound_ctrl:1
	v_pk_fma_f32 v[94:95], v[32:33], v[48:49], v[94:95] op_sel_hi:[1,0,1]
	v_pk_fma_f32 v[96:97], v[34:35], v[48:49], v[96:97] op_sel_hi:[1,0,1]
	v_pk_mul_f32 v[48:49], v[94:95], v[0:1]
	v_pk_mul_f32 v[76:77], v[94:95], v[36:37]
	v_pk_fma_f32 v[48:49], v[96:97], v[2:3], v[48:49]
	v_pk_fma_f32 v[76:77], v[96:97], v[38:39], v[76:77]
	v_add_f32_e32 v48, v48, v49
	v_add_f32_e32 v65, v76, v77
	ds_read_b128 v[0:3], v50 offset:13312
	ds_read_b128 v[28:31], v50 offset:11264
	ds_read_b128 v[24:27], v50 offset:11008
	s_waitcnt lgkmcnt(3)
	v_add_f32_dpp v48, v48, v48 quad_perm:[1,0,3,2] row_mask:0xf bank_mask:0xf bound_ctrl:1
	v_pk_mul_f32 v[44:45], v[8:9], v[42:43] op_sel_hi:[1,0]
	v_pk_mul_f32 v[46:47], v[10:11], v[42:43] op_sel_hi:[1,0]
	v_add_f32_dpp v48, v48, v48 quad_perm:[2,3,0,1] row_mask:0xf bank_mask:0xf bound_ctrl:1
	v_pk_fma_f32 v[44:45], v[94:95], v[4:5], v[44:45]
	v_pk_fma_f32 v[46:47], v[96:97], v[6:7], v[46:47]
	v_add_f32_dpp v48, v48, v48 row_half_mirror row_mask:0xf bank_mask:0xf bound_ctrl:1
	ds_read_b128 v[32:35], v50 offset:12032
	ds_read_b128 v[36:39], v50 offset:10752
	v_add_f32_dpp v48, v48, v48 row_mirror row_mask:0xf bank_mask:0xf bound_ctrl:1
	v_pk_fma_f32 v[44:45], v[12:13], v[48:49], v[44:45] op_sel_hi:[1,0,1]
	v_pk_fma_f32 v[46:47], v[14:15], v[48:49], v[46:47] op_sel_hi:[1,0,1]
	v_pk_mul_f32 v[48:49], v[44:45], v[20:21]
	v_pk_mul_f32 v[76:77], v[44:45], v[16:17]
	v_pk_fma_f32 v[48:49], v[46:47], v[22:23], v[48:49]
	v_pk_fma_f32 v[76:77], v[46:47], v[18:19], v[76:77]
	v_add_f32_e32 v48, v48, v49
	v_add_f32_e32 v66, v76, v77
	ds_read_b128 v[20:23], v50 offset:14848
	ds_read_b128 v[8:11], v50 offset:12800
	ds_read2st64_b32 v[40:41], v51 offset0:51 offset1:57
	ds_read_b128 v[4:7], v50 offset:12544
	s_waitcnt lgkmcnt(4)
	v_add_f32_dpp v48, v48, v48 quad_perm:[1,0,3,2] row_mask:0xf bank_mask:0xf bound_ctrl:1
	v_pk_mul_f32 v[94:95], v[28:29], v[42:43] op_sel:[0,1]
	v_pk_mul_f32 v[96:97], v[30:31], v[42:43] op_sel:[0,1]
	v_add_f32_dpp v48, v48, v48 quad_perm:[2,3,0,1] row_mask:0xf bank_mask:0xf bound_ctrl:1
	v_pk_fma_f32 v[94:95], v[44:45], v[24:25], v[94:95]
	v_pk_fma_f32 v[96:97], v[46:47], v[26:27], v[96:97]
	v_add_f32_dpp v48, v48, v48 row_half_mirror row_mask:0xf bank_mask:0xf bound_ctrl:1
	ds_read_b128 v[12:15], v50 offset:13568
	ds_read_b128 v[16:19], v50 offset:12288
	v_add_f32_dpp v48, v48, v48 row_mirror row_mask:0xf bank_mask:0xf bound_ctrl:1
	v_pk_fma_f32 v[94:95], v[32:33], v[48:49], v[94:95] op_sel_hi:[1,0,1]
	v_pk_fma_f32 v[96:97], v[34:35], v[48:49], v[96:97] op_sel_hi:[1,0,1]
	v_pk_mul_f32 v[48:49], v[94:95], v[0:1]
	v_pk_mul_f32 v[76:77], v[94:95], v[36:37]
	v_pk_fma_f32 v[48:49], v[96:97], v[2:3], v[48:49]
	v_pk_fma_f32 v[76:77], v[96:97], v[38:39], v[76:77]
	v_add_f32_e32 v48, v48, v49
	v_add_f32_e32 v67, v76, v77
	ds_read_b128 v[0:3], v50 offset:16384
	ds_read_b128 v[28:31], v50 offset:14336
	ds_read_b128 v[24:27], v50 offset:14080
	s_waitcnt lgkmcnt(3)
	v_add_f32_dpp v48, v48, v48 quad_perm:[1,0,3,2] row_mask:0xf bank_mask:0xf bound_ctrl:1
	v_pk_mul_f32 v[44:45], v[8:9], v[40:41] op_sel_hi:[1,0]
	v_pk_mul_f32 v[46:47], v[10:11], v[40:41] op_sel_hi:[1,0]
	v_add_f32_dpp v48, v48, v48 quad_perm:[2,3,0,1] row_mask:0xf bank_mask:0xf bound_ctrl:1
	v_pk_fma_f32 v[44:45], v[94:95], v[4:5], v[44:45]
	v_pk_fma_f32 v[46:47], v[96:97], v[6:7], v[46:47]
	v_add_f32_dpp v48, v48, v48 row_half_mirror row_mask:0xf bank_mask:0xf bound_ctrl:1
	ds_read_b128 v[32:35], v50 offset:15104
	ds_read_b128 v[36:39], v50 offset:13824
	v_add_f32_dpp v48, v48, v48 row_mirror row_mask:0xf bank_mask:0xf bound_ctrl:1
	v_pk_fma_f32 v[44:45], v[12:13], v[48:49], v[44:45] op_sel_hi:[1,0,1]
	v_pk_fma_f32 v[46:47], v[14:15], v[48:49], v[46:47] op_sel_hi:[1,0,1]
	v_pk_mul_f32 v[48:49], v[44:45], v[20:21]
	v_pk_mul_f32 v[76:77], v[44:45], v[16:17]
	v_pk_fma_f32 v[48:49], v[46:47], v[22:23], v[48:49]
	v_pk_fma_f32 v[76:77], v[46:47], v[18:19], v[76:77]
	v_add_f32_e32 v48, v48, v49
	v_add_f32_e32 v68, v76, v77
	ds_read_b128 v[20:23], v50 offset:17920
	ds_read_b128 v[8:11], v50 offset:15872
	ds_read2st64_b32 v[42:43], v51 offset0:63 offset1:69
	ds_read_b128 v[4:7], v50 offset:15616
	s_waitcnt lgkmcnt(4)
; #define LAS __attribute__((address_space(3)))
; __device__ __forceinline__ float sum16(float x) { x += dpp_f<0xB1>(x); x += dpp_f<0x4E>(x); x += dpp_f<0x141>(x); x += dpp_f<0x140>(x); return x; }
; __device__ __forceinline__ void rwkv_scan_phase(LAS unsigned char* lds, const bf16_t* RKV, const float* DEC, const float* AF, const float* k_k, const float* k_a, const float* r_k, float* BON, float* Y, int bx, const int tid) {
;     ...
;             for (int t = 0; t < SC_T; ++t) {
;                 f32x4 r4n = r4, w4n = w4, k4n = k4, a4n = a4, b4n = b4; float vvn = vv;
;                 if (t + 1 < SC_T) { const LAS unsigned char* p = base + (t + 1) * SC_TOK;
;                     r4n = *(const LAS f32x4*)(p); w4n = *(const LAS f32x4*)(p + 256); k4n = *(const LAS f32x4*)(p + 512); a4n = *(const LAS f32x4*)(p + 1024); b4n = *(const LAS f32x4*)(p + 1280);
;                     vvn = *(const LAS float*)(vbase + (t + 1) * SC_TOK); }
;                 const f32x2 a01 = {a4[0], a4[1]}, a23 = {a4[2], a4[3]}, w01 = {w4[0], w4[1]}, w23 = {w4[2], w4[3]}, b01 = {b4[0], b4[1]}, b23 = {b4[2], b4[3]}, k01 = {k4[0], k4[1]}, k23 = {k4[2], k4[3]}, r01 = {r4[0], r4[1]}, r23 = {r4[2], r4[3]};
;                 const f32x2 tsa = S01 * a01 + S23 * a23; const float sa = sum16(tsa[0] + tsa[1]);
;                 S01 = S01 * w01 + (b01 * sa + k01 * vv); S23 = S23 * w23 + (b23 * sa + k23 * vv);
;                 const f32x2 ty = S01 * r01 + S23 * r23; const float y = sum16(ty[0] + ty[1]);
;                 ykeep = ((lane & 15) == (t & 15)) ? y : ykeep;
;                 if ((t & 15) == 15) yp[(size_t)(c * SC_T + (t - 15) + (lane & 15)) * 2048] = ykeep;
;                 r4 = r4n; w4 = w4n; k4 = k4n; a4 = a4n; b4 = b4n; vv = vvn;
	v_add_f32_dpp v48, v48, v48 quad_perm:[1,0,3,2] row_mask:0xf bank_mask:0xf bound_ctrl:1
	v_pk_mul_f32 v[94:95], v[28:29], v[40:41] op_sel:[0,1]
	v_pk_mul_f32 v[96:97], v[30:31], v[40:41] op_sel:[0,1]
	v_add_f32_dpp v48, v48, v48 quad_perm:[2,3,0,1] row_mask:0xf bank_mask:0xf bound_ctrl:1
	v_pk_fma_f32 v[94:95], v[44:45], v[24:25], v[94:95]
	v_pk_fma_f32 v[96:97], v[46:47], v[26:27], v[96:97]
	v_add_f32_dpp v48, v48, v48 row_half_mirror row_mask:0xf bank_mask:0xf bound_ctrl:1
	ds_read_b128 v[12:15], v50 offset:16640
	ds_read_b128 v[16:19], v50 offset:15360
	v_add_f32_dpp v48, v48, v48 row_mirror row_mask:0xf bank_mask:0xf bound_ctrl:1
	v_pk_fma_f32 v[94:95], v[32:33], v[48:49], v[94:95] op_sel_hi:[1,0,1]
	v_pk_fma_f32 v[96:97], v[34:35], v[48:49], v[96:97] op_sel_hi:[1,0,1]
	v_pk_mul_f32 v[48:49], v[94:95], v[0:1]
	v_pk_mul_f32 v[76:77], v[94:95], v[36:37]
	v_pk_fma_f32 v[48:49], v[96:97], v[2:3], v[48:49]
	v_pk_fma_f32 v[76:77], v[96:97], v[38:39], v[76:77]
	v_add_f32_e32 v48, v48, v49
	v_add_f32_e32 v69, v76, v77
	ds_read_b128 v[0:3], v50 offset:19456
	ds_read_b128 v[28:31], v50 offset:17408
	ds_read_b128 v[24:27], v50 offset:17152
	s_waitcnt lgkmcnt(3)
	v_add_f32_dpp v48, v48, v48 quad_perm:[1,0,3,2] row_mask:0xf bank_mask:0xf bound_ctrl:1
	v_pk_mul_f32 v[44:45], v[8:9], v[42:43] op_sel_hi:[1,0]
	v_pk_mul_f32 v[46:47], v[10:11], v[42:43] op_sel_hi:[1,0]
	v_add_f32_dpp v48, v48, v48 quad_perm:[2,3,0,1] row_mask:0xf bank_mask:0xf bound_ctrl:1
	v_pk_fma_f32 v[44:45], v[94:95], v[4:5], v[44:45]
	v_pk_fma_f32 v[46:47], v[96:97], v[6:7], v[46:47]
	v_add_f32_dpp v48, v48, v48 row_half_mirror row_mask:0xf bank_mask:0xf bound_ctrl:1
	ds_read_b128 v[32:35], v50 offset:18176
	ds_read_b128 v[36:39], v50 offset:16896
	v_add_f32_dpp v48, v48, v48 row_mirror row_mask:0xf bank_mask:0xf bound_ctrl:1
	v_pk_fma_f32 v[44:45], v[12:13], v[48:49], v[44:45] op_sel_hi:[1,0,1]
	v_pk_fma_f32 v[46:47], v[14:15], v[48:49], v[46:47] op_sel_hi:[1,0,1]
	v_pk_mul_f32 v[48:49], v[44:45], v[20:21]
	v_pk_mul_f32 v[76:77], v[44:45], v[16:17]
	v_pk_fma_f32 v[48:49], v[46:47], v[22:23], v[48:49]
	v_pk_fma_f32 v[76:77], v[46:47], v[18:19], v[76:77]
	v_add_f32_e32 v48, v48, v49
	v_add_f32_e32 v70, v76, v77
	ds_read_b128 v[20:23], v50 offset:20992
	ds_read_b128 v[8:11], v50 offset:18944
	ds_read2st64_b32 v[40:41], v51 offset0:75 offset1:81
	ds_read_b128 v[4:7], v50 offset:18688
	s_waitcnt lgkmcnt(4)
	v_add_f32_dpp v48, v48, v48 quad_perm:[1,0,3,2] row_mask:0xf bank_mask:0xf bound_ctrl:1
	v_pk_mul_f32 v[94:95], v[28:29], v[42:43] op_sel:[0,1]
	v_pk_mul_f32 v[96:97], v[30:31], v[42:43] op_sel:[0,1]
	v_add_f32_dpp v48, v48, v48 quad_perm:[2,3,0,1] row_mask:0xf bank_mask:0xf bound_ctrl:1
	v_pk_fma_f32 v[94:95], v[44:45], v[24:25], v[94:95]
	v_pk_fma_f32 v[96:97], v[46:47], v[26:27], v[96:97]
	v_add_f32_dpp v48, v48, v48 row_half_mirror row_mask:0xf bank_mask:0xf bound_ctrl:1
	ds_read_b128 v[12:15], v50 offset:19712
	ds_read_b128 v[16:19], v50 offset:18432
	v_add_f32_dpp v48, v48, v48 row_mirror row_mask:0xf bank_mask:0xf bound_ctrl:1
	v_pk_fma_f32 v[94:95], v[32:33], v[48:49], v[94:95] op_sel_hi:[1,0,1]
	v_pk_fma_f32 v[96:97], v[34:35], v[48:49], v[96:97] op_sel_hi:[1,0,1]
	v_pk_mul_f32 v[48:49], v[94:95], v[0:1]
	v_pk_mul_f32 v[76:77], v[94:95], v[36:37]
	v_pk_fma_f32 v[48:49], v[96:97], v[2:3], v[48:49]
	v_pk_fma_f32 v[76:77], v[96:97], v[38:39], v[76:77]
	v_add_f32_e32 v48, v48, v49
	v_add_f32_e32 v71, v76, v77
	ds_read_b128 v[0:3], v50 offset:22528
	ds_read_b128 v[28:31], v50 offset:20480
	ds_read_b128 v[24:27], v50 offset:20224
	s_waitcnt lgkmcnt(3)
	v_add_f32_dpp v48, v48, v48 quad_perm:[1,0,3,2] row_mask:0xf bank_mask:0xf bound_ctrl:1
	v_pk_mul_f32 v[44:45], v[8:9], v[40:41] op_sel_hi:[1,0]
	v_pk_mul_f32 v[46:47], v[10:11], v[40:41] op_sel_hi:[1,0]
	v_add_f32_dpp v48, v48, v48 quad_perm:[2,3,0,1] row_mask:0xf bank_mask:0xf bound_ctrl:1
	v_pk_fma_f32 v[44:45], v[94:95], v[4:5], v[44:45]
	v_pk_fma_f32 v[46:47], v[96:97], v[6:7], v[46:47]
	v_add_f32_dpp v48, v48, v48 row_half_mirror row_mask:0xf bank_mask:0xf bound_ctrl:1
	ds_read_b128 v[32:35], v50 offset:21248
	ds_read_b128 v[36:39], v50 offset:19968
	v_add_f32_dpp v48, v48, v48 row_mirror row_mask:0xf bank_mask:0xf bound_ctrl:1
	v_pk_fma_f32 v[44:45], v[12:13], v[48:49], v[44:45] op_sel_hi:[1,0,1]
	v_pk_fma_f32 v[46:47], v[14:15], v[48:49], v[46:47] op_sel_hi:[1,0,1]
	v_pk_mul_f32 v[48:49], v[44:45], v[20:21]
	v_pk_mul_f32 v[76:77], v[44:45], v[16:17]
	v_pk_fma_f32 v[48:49], v[46:47], v[22:23], v[48:49]
	v_pk_fma_f32 v[76:77], v[46:47], v[18:19], v[76:77]
	v_add_f32_e32 v48, v48, v49
	v_add_f32_e32 v72, v76, v77
	ds_read_b128 v[20:23], v50 offset:24064
	ds_read_b128 v[8:11], v50 offset:22016
	ds_read2st64_b32 v[42:43], v51 offset0:87 offset1:93
	ds_read_b128 v[4:7], v50 offset:21760
	s_waitcnt lgkmcnt(4)
	v_add_f32_dpp v48, v48, v48 quad_perm:[1,0,3,2] row_mask:0xf bank_mask:0xf bound_ctrl:1
	v_pk_mul_f32 v[94:95], v[28:29], v[40:41] op_sel:[0,1]
	v_pk_mul_f32 v[96:97], v[30:31], v[40:41] op_sel:[0,1]
	v_add_f32_dpp v48, v48, v48 quad_perm:[2,3,0,1] row_mask:0xf bank_mask:0xf bound_ctrl:1
	v_pk_fma_f32 v[94:95], v[44:45], v[24:25], v[94:95]
	v_pk_fma_f32 v[96:97], v[46:47], v[26:27], v[96:97]
	v_add_f32_dpp v48, v48, v48 row_half_mirror row_mask:0xf bank_mask:0xf bound_ctrl:1
	ds_read_b128 v[12:15], v50 offset:22784
	ds_read_b128 v[16:19], v50 offset:21504
	v_add_f32_dpp v48, v48, v48 row_mirror row_mask:0xf bank_mask:0xf bound_ctrl:1
	v_pk_fma_f32 v[94:95], v[32:33], v[48:49], v[94:95] op_sel_hi:[1,0,1]
	v_pk_fma_f32 v[96:97], v[34:35], v[48:49], v[96:97] op_sel_hi:[1,0,1]
	v_pk_mul_f32 v[48:49], v[94:95], v[0:1]
	v_pk_mul_f32 v[76:77], v[94:95], v[36:37]
	v_pk_fma_f32 v[48:49], v[96:97], v[2:3], v[48:49]
	v_pk_fma_f32 v[76:77], v[96:97], v[38:39], v[76:77]
	v_add_f32_e32 v48, v48, v49
	v_add_f32_e32 v73, v76, v77
	ds_read_b128 v[0:3], v50 offset:25600
	ds_read_b128 v[28:31], v50 offset:23552
	ds_read_b128 v[24:27], v50 offset:23296
	s_waitcnt lgkmcnt(3)
; #define LAS __attribute__((address_space(3)))
; __device__ __forceinline__ float sum16(float x) { x += dpp_f<0xB1>(x); x += dpp_f<0x4E>(x); x += dpp_f<0x141>(x); x += dpp_f<0x140>(x); return x; }
; __device__ __forceinline__ void rwkv_scan_phase(LAS unsigned char* lds, const bf16_t* RKV, const float* DEC, const float* AF, const float* k_k, const float* k_a, const float* r_k, float* BON, float* Y, int bx, const int tid) {
;     ...
;             for (int t = 0; t < SC_T; ++t) {
;                 f32x4 r4n = r4, w4n = w4, k4n = k4, a4n = a4, b4n = b4; float vvn = vv;
;                 if (t + 1 < SC_T) { const LAS unsigned char* p = base + (t + 1) * SC_TOK;
;                     r4n = *(const LAS f32x4*)(p); w4n = *(const LAS f32x4*)(p + 256); k4n = *(const LAS f32x4*)(p + 512); a4n = *(const LAS f32x4*)(p + 1024); b4n = *(const LAS f32x4*)(p + 1280);
;                     vvn = *(const LAS float*)(vbase + (t + 1) * SC_TOK); }
;                 const f32x2 a01 = {a4[0], a4[1]}, a23 = {a4[2], a4[3]}, w01 = {w4[0], w4[1]}, w23 = {w4[2], w4[3]}, b01 = {b4[0], b4[1]}, b23 = {b4[2], b4[3]}, k01 = {k4[0], k4[1]}, k23 = {k4[2], k4[3]}, r01 = {r4[0], r4[1]}, r23 = {r4[2], r4[3]};
;                 const f32x2 tsa = S01 * a01 + S23 * a23; const float sa = sum16(tsa[0] + tsa[1]);
;                 S01 = S01 * w01 + (b01 * sa + k01 * vv); S23 = S23 * w23 + (b23 * sa + k23 * vv);
;                 const f32x2 ty = S01 * r01 + S23 * r23; const float y = sum16(ty[0] + ty[1]);
;                 ykeep = ((lane & 15) == (t & 15)) ? y : ykeep;
;                 if ((t & 15) == 15) yp[(size_t)(c * SC_T + (t - 15) + (lane & 15)) * 2048] = ykeep;
;                 r4 = r4n; w4 = w4n; k4 = k4n; a4 = a4n; b4 = b4n; vv = vvn;
;             }
	v_add_f32_dpp v48, v48, v48 quad_perm:[1,0,3,2] row_mask:0xf bank_mask:0xf bound_ctrl:1
	v_pk_mul_f32 v[44:45], v[8:9], v[42:43] op_sel_hi:[1,0]
	v_pk_mul_f32 v[46:47], v[10:11], v[42:43] op_sel_hi:[1,0]
	v_add_f32_dpp v48, v48, v48 quad_perm:[2,3,0,1] row_mask:0xf bank_mask:0xf bound_ctrl:1
	v_pk_fma_f32 v[44:45], v[94:95], v[4:5], v[44:45]
	v_pk_fma_f32 v[46:47], v[96:97], v[6:7], v[46:47]
	v_add_f32_dpp v48, v48, v48 row_half_mirror row_mask:0xf bank_mask:0xf bound_ctrl:1
	ds_read_b128 v[32:35], v50 offset:24320
	ds_read_b128 v[36:39], v50 offset:23040
	v_add_f32_dpp v48, v48, v48 row_mirror row_mask:0xf bank_mask:0xf bound_ctrl:1
	v_pk_fma_f32 v[44:45], v[12:13], v[48:49], v[44:45] op_sel_hi:[1,0,1]
	v_pk_fma_f32 v[46:47], v[14:15], v[48:49], v[46:47] op_sel_hi:[1,0,1]
	v_pk_mul_f32 v[48:49], v[44:45], v[20:21]
	v_pk_mul_f32 v[76:77], v[44:45], v[16:17]
	v_pk_fma_f32 v[48:49], v[46:47], v[22:23], v[48:49]
	v_pk_fma_f32 v[76:77], v[46:47], v[18:19], v[76:77]
	v_add_f32_e32 v48, v48, v49
	v_add_f32_e32 v74, v76, v77
	ds_read_b128 v[20:23], v50 offset:27136
	ds_read_b128 v[8:11], v50 offset:25088
	ds_read2st64_b32 v[40:41], v51 offset0:99 offset1:105
	ds_read_b128 v[4:7], v50 offset:24832
	s_waitcnt lgkmcnt(4)
	v_add_f32_dpp v48, v48, v48 quad_perm:[1,0,3,2] row_mask:0xf bank_mask:0xf bound_ctrl:1
	v_pk_mul_f32 v[94:95], v[28:29], v[42:43] op_sel:[0,1]
	v_pk_mul_f32 v[96:97], v[30:31], v[42:43] op_sel:[0,1]
	v_add_f32_dpp v48, v48, v48 quad_perm:[2,3,0,1] row_mask:0xf bank_mask:0xf bound_ctrl:1
	v_pk_fma_f32 v[94:95], v[44:45], v[24:25], v[94:95]
	v_pk_fma_f32 v[96:97], v[46:47], v[26:27], v[96:97]
	v_add_f32_dpp v48, v48, v48 row_half_mirror row_mask:0xf bank_mask:0xf bound_ctrl:1
	ds_read_b128 v[12:15], v50 offset:25856
	ds_read_b128 v[16:19], v50 offset:24576
	v_add_f32_dpp v48, v48, v48 row_mirror row_mask:0xf bank_mask:0xf bound_ctrl:1
	v_pk_fma_f32 v[94:95], v[32:33], v[48:49], v[94:95] op_sel_hi:[1,0,1]
	v_pk_fma_f32 v[96:97], v[34:35], v[48:49], v[96:97] op_sel_hi:[1,0,1]
	v_pk_mul_f32 v[48:49], v[94:95], v[0:1]
	v_pk_mul_f32 v[76:77], v[94:95], v[36:37]
	v_pk_fma_f32 v[48:49], v[96:97], v[2:3], v[48:49]
	v_pk_fma_f32 v[76:77], v[96:97], v[38:39], v[76:77]
	v_add_f32_e32 v48, v48, v49
	v_add_f32_e32 v75, v76, v77
	v_add_f32_dpp v60, v60, v60 row_mirror row_mask:0xf bank_mask:0x3 bound_ctrl:1
	v_add_f32_dpp v60, v68, v68 row_mirror row_mask:0xf bank_mask:0xc bound_ctrl:1
	v_add_f32_dpp v61, v61, v61 row_mirror row_mask:0xf bank_mask:0x3 bound_ctrl:1
	v_add_f32_dpp v61, v69, v69 row_mirror row_mask:0xf bank_mask:0xc bound_ctrl:1
	v_add_f32_dpp v62, v62, v62 row_mirror row_mask:0xf bank_mask:0x3 bound_ctrl:1
	v_add_f32_dpp v62, v70, v70 row_mirror row_mask:0xf bank_mask:0xc bound_ctrl:1
	v_add_f32_dpp v63, v63, v63 row_mirror row_mask:0xf bank_mask:0x3 bound_ctrl:1
	v_add_f32_dpp v63, v71, v71 row_mirror row_mask:0xf bank_mask:0xc bound_ctrl:1
	v_add_f32_dpp v64, v64, v64 row_mirror row_mask:0xf bank_mask:0x3 bound_ctrl:1
	v_add_f32_dpp v64, v72, v72 row_mirror row_mask:0xf bank_mask:0xc bound_ctrl:1
	v_add_f32_dpp v65, v65, v65 row_mirror row_mask:0xf bank_mask:0x3 bound_ctrl:1
	v_add_f32_dpp v65, v73, v73 row_mirror row_mask:0xf bank_mask:0xc bound_ctrl:1
	v_add_f32_dpp v66, v66, v66 row_mirror row_mask:0xf bank_mask:0x3 bound_ctrl:1
	v_add_f32_dpp v66, v74, v74 row_mirror row_mask:0xf bank_mask:0xc bound_ctrl:1
	v_add_f32_dpp v67, v67, v67 row_mirror row_mask:0xf bank_mask:0x3 bound_ctrl:1
	v_add_f32_dpp v67, v75, v75 row_mirror row_mask:0xf bank_mask:0xc bound_ctrl:1
	v_add_f32_dpp v60, v60, v60 row_half_mirror row_mask:0xf bank_mask:0x5 bound_ctrl:1
	v_add_f32_dpp v60, v64, v64 row_half_mirror row_mask:0xf bank_mask:0xa bound_ctrl:1
	v_add_f32_dpp v61, v61, v61 row_half_mirror row_mask:0xf bank_mask:0x5 bound_ctrl:1
	v_add_f32_dpp v61, v65, v65 row_half_mirror row_mask:0xf bank_mask:0xa bound_ctrl:1
	v_add_f32_dpp v62, v62, v62 row_half_mirror row_mask:0xf bank_mask:0x5 bound_ctrl:1
	v_add_f32_dpp v62, v66, v66 row_half_mirror row_mask:0xf bank_mask:0xa bound_ctrl:1
	v_add_f32_dpp v63, v63, v63 row_half_mirror row_mask:0xf bank_mask:0x5 bound_ctrl:1
	v_add_f32_dpp v63, v67, v67 row_half_mirror row_mask:0xf bank_mask:0xa bound_ctrl:1
	v_cndmask_b32_e64 v76, v62, v60, s[46:47]
	v_cndmask_b32_e64 v77, v63, v61, s[46:47]
	v_cndmask_b32_e64 v78, v60, v62, s[46:47]
	v_cndmask_b32_e64 v79, v61, v63, s[46:47]
	v_add_f32_dpp v60, v76, v78 quad_perm:[2,3,0,1] row_mask:0xf bank_mask:0xf bound_ctrl:1
	v_add_f32_dpp v61, v77, v79 quad_perm:[2,3,0,1] row_mask:0xf bank_mask:0xf bound_ctrl:1
	v_cndmask_b32_e64 v76, v61, v60, s[40:41]
	v_cndmask_b32_e64 v78, v60, v61, s[40:41]
	s_nop 1
	v_add_f32_dpp v60, v76, v78 quad_perm:[1,0,3,2] row_mask:0xf bank_mask:0xf bound_ctrl:1
	global_store_dword v[92:93], v60, off
	ds_read_b128 v[0:3], v50 offset:28672
	ds_read_b128 v[28:31], v50 offset:26624
	ds_read_b128 v[24:27], v50 offset:26368
	s_waitcnt lgkmcnt(3)
	v_add_f32_dpp v48, v48, v48 quad_perm:[1,0,3,2] row_mask:0xf bank_mask:0xf bound_ctrl:1
	v_pk_mul_f32 v[44:45], v[8:9], v[40:41] op_sel_hi:[1,0]
	v_pk_mul_f32 v[46:47], v[10:11], v[40:41] op_sel_hi:[1,0]
	v_add_f32_dpp v48, v48, v48 quad_perm:[2,3,0,1] row_mask:0xf bank_mask:0xf bound_ctrl:1
	v_pk_fma_f32 v[44:45], v[94:95], v[4:5], v[44:45]
	v_pk_fma_f32 v[46:47], v[96:97], v[6:7], v[46:47]
	v_add_f32_dpp v48, v48, v48 row_half_mirror row_mask:0xf bank_mask:0xf bound_ctrl:1
	ds_read_b128 v[32:35], v50 offset:27392
	ds_read_b128 v[36:39], v50 offset:26112
	v_add_f32_dpp v48, v48, v48 row_mirror row_mask:0xf bank_mask:0xf bound_ctrl:1
	v_pk_fma_f32 v[44:45], v[12:13], v[48:49], v[44:45] op_sel_hi:[1,0,1]
	v_pk_fma_f32 v[46:47], v[14:15], v[48:49], v[46:47] op_sel_hi:[1,0,1]
	v_pk_mul_f32 v[48:49], v[44:45], v[20:21]
	v_pk_mul_f32 v[76:77], v[44:45], v[16:17]
	v_pk_fma_f32 v[48:49], v[46:47], v[22:23], v[48:49]
	v_pk_fma_f32 v[76:77], v[46:47], v[18:19], v[76:77]
	v_add_f32_e32 v48, v48, v49
	v_add_f32_e32 v60, v76, v77
	ds_read_b128 v[20:23], v50 offset:30208
	ds_read_b128 v[8:11], v50 offset:28160
	ds_read2st64_b32 v[42:43], v51 offset0:111 offset1:117
	ds_read_b128 v[4:7], v50 offset:27904
	s_waitcnt lgkmcnt(4)
; #define LAS __attribute__((address_space(3)))
; __device__ __forceinline__ float sum16(float x) { x += dpp_f<0xB1>(x); x += dpp_f<0x4E>(x); x += dpp_f<0x141>(x); x += dpp_f<0x140>(x); return x; }
; __device__ __forceinline__ void rwkv_scan_phase(LAS unsigned char* lds, const bf16_t* RKV, const float* DEC, const float* AF, const float* k_k, const float* k_a, const float* r_k, float* BON, float* Y, int bx, const int tid) {
;     ...
;             for (int t = 0; t < SC_T; ++t) {
;                 f32x4 r4n = r4, w4n = w4, k4n = k4, a4n = a4, b4n = b4; float vvn = vv;
;                 if (t + 1 < SC_T) { const LAS unsigned char* p = base + (t + 1) * SC_TOK;
;                     r4n = *(const LAS f32x4*)(p); w4n = *(const LAS f32x4*)(p + 256); k4n = *(const LAS f32x4*)(p + 512); a4n = *(const LAS f32x4*)(p + 1024); b4n = *(const LAS f32x4*)(p + 1280);
;                     vvn = *(const LAS float*)(vbase + (t + 1) * SC_TOK); }
;                 const f32x2 a01 = {a4[0], a4[1]}, a23 = {a4[2], a4[3]}, w01 = {w4[0], w4[1]}, w23 = {w4[2], w4[3]}, b01 = {b4[0], b4[1]}, b23 = {b4[2], b4[3]}, k01 = {k4[0], k4[1]}, k23 = {k4[2], k4[3]}, r01 = {r4[0], r4[1]}, r23 = {r4[2], r4[3]};
;                 const f32x2 tsa = S01 * a01 + S23 * a23; const float sa = sum16(tsa[0] + tsa[1]);
;                 S01 = S01 * w01 + (b01 * sa + k01 * vv); S23 = S23 * w23 + (b23 * sa + k23 * vv);
;                 const f32x2 ty = S01 * r01 + S23 * r23; const float y = sum16(ty[0] + ty[1]);
;                 ykeep = ((lane & 15) == (t & 15)) ? y : ykeep;
;                 if ((t & 15) == 15) yp[(size_t)(c * SC_T + (t - 15) + (lane & 15)) * 2048] = ykeep;
;                 r4 = r4n; w4 = w4n; k4 = k4n; a4 = a4n; b4 = b4n; vv = vvn;
	v_add_f32_dpp v48, v48, v48 quad_perm:[1,0,3,2] row_mask:0xf bank_mask:0xf bound_ctrl:1
	v_pk_mul_f32 v[94:95], v[28:29], v[40:41] op_sel:[0,1]
	v_pk_mul_f32 v[96:97], v[30:31], v[40:41] op_sel:[0,1]
	v_add_f32_dpp v48, v48, v48 quad_perm:[2,3,0,1] row_mask:0xf bank_mask:0xf bound_ctrl:1
	v_pk_fma_f32 v[94:95], v[44:45], v[24:25], v[94:95]
	v_pk_fma_f32 v[96:97], v[46:47], v[26:27], v[96:97]
	v_add_f32_dpp v48, v48, v48 row_half_mirror row_mask:0xf bank_mask:0xf bound_ctrl:1
	ds_read_b128 v[12:15], v50 offset:28928
	ds_read_b128 v[16:19], v50 offset:27648
	v_add_f32_dpp v48, v48, v48 row_mirror row_mask:0xf bank_mask:0xf bound_ctrl:1
	v_pk_fma_f32 v[94:95], v[32:33], v[48:49], v[94:95] op_sel_hi:[1,0,1]
	v_pk_fma_f32 v[96:97], v[34:35], v[48:49], v[96:97] op_sel_hi:[1,0,1]
	v_pk_mul_f32 v[48:49], v[94:95], v[0:1]
	v_pk_mul_f32 v[76:77], v[94:95], v[36:37]
	v_pk_fma_f32 v[48:49], v[96:97], v[2:3], v[48:49]
	v_pk_fma_f32 v[76:77], v[96:97], v[38:39], v[76:77]
	v_add_f32_e32 v48, v48, v49
	v_add_f32_e32 v61, v76, v77
	ds_read_b128 v[0:3], v50 offset:31744
	ds_read_b128 v[28:31], v50 offset:29696
	ds_read_b128 v[24:27], v50 offset:29440
	s_waitcnt lgkmcnt(3)
	v_add_f32_dpp v48, v48, v48 quad_perm:[1,0,3,2] row_mask:0xf bank_mask:0xf bound_ctrl:1
	v_pk_mul_f32 v[44:45], v[8:9], v[42:43] op_sel_hi:[1,0]
	v_pk_mul_f32 v[46:47], v[10:11], v[42:43] op_sel_hi:[1,0]
	v_add_f32_dpp v48, v48, v48 quad_perm:[2,3,0,1] row_mask:0xf bank_mask:0xf bound_ctrl:1
	v_pk_fma_f32 v[44:45], v[94:95], v[4:5], v[44:45]
	v_pk_fma_f32 v[46:47], v[96:97], v[6:7], v[46:47]
	v_add_f32_dpp v48, v48, v48 row_half_mirror row_mask:0xf bank_mask:0xf bound_ctrl:1
	ds_read_b128 v[32:35], v50 offset:30464
	ds_read_b128 v[36:39], v50 offset:29184
	v_add_f32_dpp v48, v48, v48 row_mirror row_mask:0xf bank_mask:0xf bound_ctrl:1
	v_pk_fma_f32 v[44:45], v[12:13], v[48:49], v[44:45] op_sel_hi:[1,0,1]
	v_pk_fma_f32 v[46:47], v[14:15], v[48:49], v[46:47] op_sel_hi:[1,0,1]
	v_pk_mul_f32 v[48:49], v[44:45], v[20:21]
	v_pk_mul_f32 v[76:77], v[44:45], v[16:17]
	v_pk_fma_f32 v[48:49], v[46:47], v[22:23], v[48:49]
	v_pk_fma_f32 v[76:77], v[46:47], v[18:19], v[76:77]
	v_add_f32_e32 v48, v48, v49
	v_add_f32_e32 v62, v76, v77
	ds_read_b128 v[20:23], v50 offset:33280
	ds_read_b128 v[8:11], v50 offset:31232
	ds_read2st64_b32 v[40:41], v51 offset0:123 offset1:129
	ds_read_b128 v[4:7], v50 offset:30976
	s_waitcnt lgkmcnt(4)
	v_add_f32_dpp v48, v48, v48 quad_perm:[1,0,3,2] row_mask:0xf bank_mask:0xf bound_ctrl:1
	v_pk_mul_f32 v[94:95], v[28:29], v[42:43] op_sel:[0,1]
	v_pk_mul_f32 v[96:97], v[30:31], v[42:43] op_sel:[0,1]
	v_add_f32_dpp v48, v48, v48 quad_perm:[2,3,0,1] row_mask:0xf bank_mask:0xf bound_ctrl:1
	v_pk_fma_f32 v[94:95], v[44:45], v[24:25], v[94:95]
	v_pk_fma_f32 v[96:97], v[46:47], v[26:27], v[96:97]
	v_add_f32_dpp v48, v48, v48 row_half_mirror row_mask:0xf bank_mask:0xf bound_ctrl:1
	ds_read_b128 v[12:15], v50 offset:32000
	ds_read_b128 v[16:19], v50 offset:30720
	v_add_f32_dpp v48, v48, v48 row_mirror row_mask:0xf bank_mask:0xf bound_ctrl:1
	v_pk_fma_f32 v[94:95], v[32:33], v[48:49], v[94:95] op_sel_hi:[1,0,1]
	v_pk_fma_f32 v[96:97], v[34:35], v[48:49], v[96:97] op_sel_hi:[1,0,1]
	v_pk_mul_f32 v[48:49], v[94:95], v[0:1]
	v_pk_mul_f32 v[76:77], v[94:95], v[36:37]
	v_pk_fma_f32 v[48:49], v[96:97], v[2:3], v[48:49]
	v_pk_fma_f32 v[76:77], v[96:97], v[38:39], v[76:77]
	v_add_f32_e32 v48, v48, v49
	v_add_f32_e32 v63, v76, v77
	ds_read_b128 v[0:3], v50 offset:34816
	ds_read_b128 v[28:31], v50 offset:32768
	ds_read_b128 v[24:27], v50 offset:32512
	s_waitcnt lgkmcnt(3)
	v_add_f32_dpp v48, v48, v48 quad_perm:[1,0,3,2] row_mask:0xf bank_mask:0xf bound_ctrl:1
	v_pk_mul_f32 v[44:45], v[8:9], v[40:41] op_sel_hi:[1,0]
	v_pk_mul_f32 v[46:47], v[10:11], v[40:41] op_sel_hi:[1,0]
	v_add_f32_dpp v48, v48, v48 quad_perm:[2,3,0,1] row_mask:0xf bank_mask:0xf bound_ctrl:1
	v_pk_fma_f32 v[44:45], v[94:95], v[4:5], v[44:45]
	v_pk_fma_f32 v[46:47], v[96:97], v[6:7], v[46:47]
	v_add_f32_dpp v48, v48, v48 row_half_mirror row_mask:0xf bank_mask:0xf bound_ctrl:1
	ds_read_b128 v[32:35], v50 offset:33536
	ds_read_b128 v[36:39], v50 offset:32256
	v_add_f32_dpp v48, v48, v48 row_mirror row_mask:0xf bank_mask:0xf bound_ctrl:1
	v_pk_fma_f32 v[44:45], v[12:13], v[48:49], v[44:45] op_sel_hi:[1,0,1]
	v_pk_fma_f32 v[46:47], v[14:15], v[48:49], v[46:47] op_sel_hi:[1,0,1]
	v_pk_mul_f32 v[48:49], v[44:45], v[20:21]
	v_pk_mul_f32 v[76:77], v[44:45], v[16:17]
	v_pk_fma_f32 v[48:49], v[46:47], v[22:23], v[48:49]
	v_pk_fma_f32 v[76:77], v[46:47], v[18:19], v[76:77]
	v_add_f32_e32 v48, v48, v49
	v_add_f32_e32 v64, v76, v77
	ds_read_b128 v[20:23], v50 offset:36352
	ds_read_b128 v[8:11], v50 offset:34304
	ds_read2st64_b32 v[42:43], v51 offset0:135 offset1:141
	ds_read_b128 v[4:7], v50 offset:34048
	s_waitcnt lgkmcnt(4)
	v_add_f32_dpp v48, v48, v48 quad_perm:[1,0,3,2] row_mask:0xf bank_mask:0xf bound_ctrl:1
	v_pk_mul_f32 v[94:95], v[28:29], v[40:41] op_sel:[0,1]
	v_pk_mul_f32 v[96:97], v[30:31], v[40:41] op_sel:[0,1]
	v_add_f32_dpp v48, v48, v48 quad_perm:[2,3,0,1] row_mask:0xf bank_mask:0xf bound_ctrl:1
	v_pk_fma_f32 v[94:95], v[44:45], v[24:25], v[94:95]
	v_pk_fma_f32 v[96:97], v[46:47], v[26:27], v[96:97]
	v_add_f32_dpp v48, v48, v48 row_half_mirror row_mask:0xf bank_mask:0xf bound_ctrl:1
	ds_read_b128 v[12:15], v50 offset:35072
	ds_read_b128 v[16:19], v50 offset:33792
	v_add_f32_dpp v48, v48, v48 row_mirror row_mask:0xf bank_mask:0xf bound_ctrl:1
	v_pk_fma_f32 v[94:95], v[32:33], v[48:49], v[94:95] op_sel_hi:[1,0,1]
	v_pk_fma_f32 v[96:97], v[34:35], v[48:49], v[96:97] op_sel_hi:[1,0,1]
	v_pk_mul_f32 v[48:49], v[94:95], v[0:1]
	v_pk_mul_f32 v[76:77], v[94:95], v[36:37]
	v_pk_fma_f32 v[48:49], v[96:97], v[2:3], v[48:49]
	v_pk_fma_f32 v[76:77], v[96:97], v[38:39], v[76:77]
	v_add_f32_e32 v48, v48, v49
	v_add_f32_e32 v65, v76, v77
	ds_read_b128 v[0:3], v50 offset:37888
	ds_read_b128 v[28:31], v50 offset:35840
	ds_read_b128 v[24:27], v50 offset:35584
	s_waitcnt lgkmcnt(3)
; #define LAS __attribute__((address_space(3)))
; __device__ __forceinline__ float sum16(float x) { x += dpp_f<0xB1>(x); x += dpp_f<0x4E>(x); x += dpp_f<0x141>(x); x += dpp_f<0x140>(x); return x; }
; __device__ __forceinline__ void rwkv_scan_phase(LAS unsigned char* lds, const bf16_t* RKV, const float* DEC, const float* AF, const float* k_k, const float* k_a, const float* r_k, float* BON, float* Y, int bx, const int tid) {
;     ...
;             for (int t = 0; t < SC_T; ++t) {
;                 f32x4 r4n = r4, w4n = w4, k4n = k4, a4n = a4, b4n = b4; float vvn = vv;
;                 if (t + 1 < SC_T) { const LAS unsigned char* p = base + (t + 1) * SC_TOK;
;                     r4n = *(const LAS f32x4*)(p); w4n = *(const LAS f32x4*)(p + 256); k4n = *(const LAS f32x4*)(p + 512); a4n = *(const LAS f32x4*)(p + 1024); b4n = *(const LAS f32x4*)(p + 1280);
;                     vvn = *(const LAS float*)(vbase + (t + 1) * SC_TOK); }
;                 const f32x2 a01 = {a4[0], a4[1]}, a23 = {a4[2], a4[3]}, w01 = {w4[0], w4[1]}, w23 = {w4[2], w4[3]}, b01 = {b4[0], b4[1]}, b23 = {b4[2], b4[3]}, k01 = {k4[0], k4[1]}, k23 = {k4[2], k4[3]}, r01 = {r4[0], r4[1]}, r23 = {r4[2], r4[3]};
;                 const f32x2 tsa = S01 * a01 + S23 * a23; const float sa = sum16(tsa[0] + tsa[1]);
;                 S01 = S01 * w01 + (b01 * sa + k01 * vv); S23 = S23 * w23 + (b23 * sa + k23 * vv);
;                 const f32x2 ty = S01 * r01 + S23 * r23; const float y = sum16(ty[0] + ty[1]);
	v_add_f32_dpp v48, v48, v48 quad_perm:[1,0,3,2] row_mask:0xf bank_mask:0xf bound_ctrl:1
	v_pk_mul_f32 v[44:45], v[8:9], v[42:43] op_sel_hi:[1,0]
	v_pk_mul_f32 v[46:47], v[10:11], v[42:43] op_sel_hi:[1,0]
	v_add_f32_dpp v48, v48, v48 quad_perm:[2,3,0,1] row_mask:0xf bank_mask:0xf bound_ctrl:1
	v_pk_fma_f32 v[44:45], v[94:95], v[4:5], v[44:45]
	v_pk_fma_f32 v[46:47], v[96:97], v[6:7], v[46:47]
	v_add_f32_dpp v48, v48, v48 row_half_mirror row_mask:0xf bank_mask:0xf bound_ctrl:1
	ds_read_b128 v[32:35], v50 offset:36608
	ds_read_b128 v[36:39], v50 offset:35328
	v_add_f32_dpp v48, v48, v48 row_mirror row_mask:0xf bank_mask:0xf bound_ctrl:1
	v_pk_fma_f32 v[44:45], v[12:13], v[48:49], v[44:45] op_sel_hi:[1,0,1]
	v_pk_fma_f32 v[46:47], v[14:15], v[48:49], v[46:47] op_sel_hi:[1,0,1]
	v_pk_mul_f32 v[48:49], v[44:45], v[20:21]
	v_pk_mul_f32 v[76:77], v[44:45], v[16:17]
	v_pk_fma_f32 v[48:49], v[46:47], v[22:23], v[48:49]
	v_pk_fma_f32 v[76:77], v[46:47], v[18:19], v[76:77]
	v_add_f32_e32 v48, v48, v49
	v_add_f32_e32 v66, v76, v77
	ds_read_b128 v[20:23], v50 offset:39424
	ds_read_b128 v[8:11], v50 offset:37376
	ds_read2st64_b32 v[40:41], v51 offset0:147 offset1:153
	ds_read_b128 v[4:7], v50 offset:37120
	s_waitcnt lgkmcnt(4)
	v_add_f32_dpp v48, v48, v48 quad_perm:[1,0,3,2] row_mask:0xf bank_mask:0xf bound_ctrl:1
	v_pk_mul_f32 v[94:95], v[28:29], v[42:43] op_sel:[0,1]
	v_pk_mul_f32 v[96:97], v[30:31], v[42:43] op_sel:[0,1]
	v_add_f32_dpp v48, v48, v48 quad_perm:[2,3,0,1] row_mask:0xf bank_mask:0xf bound_ctrl:1
	v_pk_fma_f32 v[94:95], v[44:45], v[24:25], v[94:95]
	v_pk_fma_f32 v[96:97], v[46:47], v[26:27], v[96:97]
	v_add_f32_dpp v48, v48, v48 row_half_mirror row_mask:0xf bank_mask:0xf bound_ctrl:1
	ds_read_b128 v[12:15], v50 offset:38144
	ds_read_b128 v[16:19], v50 offset:36864
	v_add_f32_dpp v48, v48, v48 row_mirror row_mask:0xf bank_mask:0xf bound_ctrl:1
	v_pk_fma_f32 v[94:95], v[32:33], v[48:49], v[94:95] op_sel_hi:[1,0,1]
	v_pk_fma_f32 v[96:97], v[34:35], v[48:49], v[96:97] op_sel_hi:[1,0,1]
	v_pk_mul_f32 v[48:49], v[94:95], v[0:1]
	v_pk_mul_f32 v[76:77], v[94:95], v[36:37]
	v_pk_fma_f32 v[48:49], v[96:97], v[2:3], v[48:49]
	v_pk_fma_f32 v[76:77], v[96:97], v[38:39], v[76:77]
	v_add_f32_e32 v48, v48, v49
	v_add_f32_e32 v67, v76, v77
	ds_read_b128 v[0:3], v50 offset:40960
	ds_read_b128 v[28:31], v50 offset:38912
	ds_read_b128 v[24:27], v50 offset:38656
	s_waitcnt lgkmcnt(3)
	v_add_f32_dpp v48, v48, v48 quad_perm:[1,0,3,2] row_mask:0xf bank_mask:0xf bound_ctrl:1
	v_pk_mul_f32 v[44:45], v[8:9], v[40:41] op_sel_hi:[1,0]
	v_pk_mul_f32 v[46:47], v[10:11], v[40:41] op_sel_hi:[1,0]
	v_add_f32_dpp v48, v48, v48 quad_perm:[2,3,0,1] row_mask:0xf bank_mask:0xf bound_ctrl:1
	v_pk_fma_f32 v[44:45], v[94:95], v[4:5], v[44:45]
	v_pk_fma_f32 v[46:47], v[96:97], v[6:7], v[46:47]
	v_add_f32_dpp v48, v48, v48 row_half_mirror row_mask:0xf bank_mask:0xf bound_ctrl:1
	ds_read_b128 v[32:35], v50 offset:39680
	ds_read_b128 v[36:39], v50 offset:38400
	v_add_f32_dpp v48, v48, v48 row_mirror row_mask:0xf bank_mask:0xf bound_ctrl:1
	v_pk_fma_f32 v[44:45], v[12:13], v[48:49], v[44:45] op_sel_hi:[1,0,1]
	v_pk_fma_f32 v[46:47], v[14:15], v[48:49], v[46:47] op_sel_hi:[1,0,1]
	v_pk_mul_f32 v[48:49], v[44:45], v[20:21]
	v_pk_mul_f32 v[76:77], v[44:45], v[16:17]
	v_pk_fma_f32 v[48:49], v[46:47], v[22:23], v[48:49]
	v_pk_fma_f32 v[76:77], v[46:47], v[18:19], v[76:77]
	v_add_f32_e32 v48, v48, v49
	v_add_f32_e32 v68, v76, v77
	ds_read_b128 v[20:23], v50 offset:42496
	ds_read_b128 v[8:11], v50 offset:40448
	ds_read2st64_b32 v[42:43], v51 offset0:159 offset1:165
	ds_read_b128 v[4:7], v50 offset:40192
	s_waitcnt lgkmcnt(4)
	v_add_f32_dpp v48, v48, v48 quad_perm:[1,0,3,2] row_mask:0xf bank_mask:0xf bound_ctrl:1
	v_pk_mul_f32 v[94:95], v[28:29], v[40:41] op_sel:[0,1]
	v_pk_mul_f32 v[96:97], v[30:31], v[40:41] op_sel:[0,1]
	v_add_f32_dpp v48, v48, v48 quad_perm:[2,3,0,1] row_mask:0xf bank_mask:0xf bound_ctrl:1
	v_pk_fma_f32 v[94:95], v[44:45], v[24:25], v[94:95]
	v_pk_fma_f32 v[96:97], v[46:47], v[26:27], v[96:97]
	v_add_f32_dpp v48, v48, v48 row_half_mirror row_mask:0xf bank_mask:0xf bound_ctrl:1
	ds_read_b128 v[12:15], v50 offset:41216
	ds_read_b128 v[16:19], v50 offset:39936
	v_add_f32_dpp v48, v48, v48 row_mirror row_mask:0xf bank_mask:0xf bound_ctrl:1
	v_pk_fma_f32 v[94:95], v[32:33], v[48:49], v[94:95] op_sel_hi:[1,0,1]
	v_pk_fma_f32 v[96:97], v[34:35], v[48:49], v[96:97] op_sel_hi:[1,0,1]
	v_pk_mul_f32 v[48:49], v[94:95], v[0:1]
	v_pk_mul_f32 v[76:77], v[94:95], v[36:37]
	v_pk_fma_f32 v[48:49], v[96:97], v[2:3], v[48:49]
	v_pk_fma_f32 v[76:77], v[96:97], v[38:39], v[76:77]
	v_add_f32_e32 v48, v48, v49
	v_add_f32_e32 v69, v76, v77
	ds_read_b128 v[0:3], v50 offset:44032
	ds_read_b128 v[28:31], v50 offset:41984
	ds_read_b128 v[24:27], v50 offset:41728
	s_waitcnt lgkmcnt(3)
	v_add_f32_dpp v48, v48, v48 quad_perm:[1,0,3,2] row_mask:0xf bank_mask:0xf bound_ctrl:1
	v_pk_mul_f32 v[44:45], v[8:9], v[42:43] op_sel_hi:[1,0]
	v_pk_mul_f32 v[46:47], v[10:11], v[42:43] op_sel_hi:[1,0]
	v_add_f32_dpp v48, v48, v48 quad_perm:[2,3,0,1] row_mask:0xf bank_mask:0xf bound_ctrl:1
	v_pk_fma_f32 v[44:45], v[94:95], v[4:5], v[44:45]
	v_pk_fma_f32 v[46:47], v[96:97], v[6:7], v[46:47]
	v_add_f32_dpp v48, v48, v48 row_half_mirror row_mask:0xf bank_mask:0xf bound_ctrl:1
	ds_read_b128 v[32:35], v50 offset:42752
	ds_read_b128 v[36:39], v50 offset:41472
	v_add_f32_dpp v48, v48, v48 row_mirror row_mask:0xf bank_mask:0xf bound_ctrl:1
	v_pk_fma_f32 v[44:45], v[12:13], v[48:49], v[44:45] op_sel_hi:[1,0,1]
	v_pk_fma_f32 v[46:47], v[14:15], v[48:49], v[46:47] op_sel_hi:[1,0,1]
	v_pk_mul_f32 v[48:49], v[44:45], v[20:21]
	v_pk_mul_f32 v[76:77], v[44:45], v[16:17]
	v_pk_fma_f32 v[48:49], v[46:47], v[22:23], v[48:49]
	v_pk_fma_f32 v[76:77], v[46:47], v[18:19], v[76:77]
	v_add_f32_e32 v48, v48, v49
	v_add_f32_e32 v70, v76, v77
	ds_read_b128 v[20:23], v50 offset:45568
	ds_read_b128 v[8:11], v50 offset:43520
	ds_read2st64_b32 v[40:41], v51 offset0:171 offset1:177
	ds_read_b128 v[4:7], v50 offset:43264
	s_waitcnt lgkmcnt(4)
; #define LAS __attribute__((address_space(3)))
; __device__ __forceinline__ float sum16(float x) { x += dpp_f<0xB1>(x); x += dpp_f<0x4E>(x); x += dpp_f<0x141>(x); x += dpp_f<0x140>(x); return x; }
; __device__ __forceinline__ void rwkv_scan_phase(LAS unsigned char* lds, const bf16_t* RKV, const float* DEC, const float* AF, const float* k_k, const float* k_a, const float* r_k, float* BON, float* Y, int bx, const int tid) {
;     ...
;             for (int t = 0; t < SC_T; ++t) {
;                 f32x4 r4n = r4, w4n = w4, k4n = k4, a4n = a4, b4n = b4; float vvn = vv;
;                 if (t + 1 < SC_T) { const LAS unsigned char* p = base + (t + 1) * SC_TOK;
;                     r4n = *(const LAS f32x4*)(p); w4n = *(const LAS f32x4*)(p + 256); k4n = *(const LAS f32x4*)(p + 512); a4n = *(const LAS f32x4*)(p + 1024); b4n = *(const LAS f32x4*)(p + 1280);
;                     vvn = *(const LAS float*)(vbase + (t + 1) * SC_TOK); }
;                 const f32x2 a01 = {a4[0], a4[1]}, a23 = {a4[2], a4[3]}, w01 = {w4[0], w4[1]}, w23 = {w4[2], w4[3]}, b01 = {b4[0], b4[1]}, b23 = {b4[2], b4[3]}, k01 = {k4[0], k4[1]}, k23 = {k4[2], k4[3]}, r01 = {r4[0], r4[1]}, r23 = {r4[2], r4[3]};
;                 const f32x2 tsa = S01 * a01 + S23 * a23; const float sa = sum16(tsa[0] + tsa[1]);
;                 S01 = S01 * w01 + (b01 * sa + k01 * vv); S23 = S23 * w23 + (b23 * sa + k23 * vv);
;                 const f32x2 ty = S01 * r01 + S23 * r23; const float y = sum16(ty[0] + ty[1]);
	v_add_f32_dpp v48, v48, v48 quad_perm:[1,0,3,2] row_mask:0xf bank_mask:0xf bound_ctrl:1
	v_pk_mul_f32 v[94:95], v[28:29], v[42:43] op_sel:[0,1]
	v_pk_mul_f32 v[96:97], v[30:31], v[42:43] op_sel:[0,1]
	v_add_f32_dpp v48, v48, v48 quad_perm:[2,3,0,1] row_mask:0xf bank_mask:0xf bound_ctrl:1
	v_pk_fma_f32 v[94:95], v[44:45], v[24:25], v[94:95]
	v_pk_fma_f32 v[96:97], v[46:47], v[26:27], v[96:97]
	v_add_f32_dpp v48, v48, v48 row_half_mirror row_mask:0xf bank_mask:0xf bound_ctrl:1
	ds_read_b128 v[12:15], v50 offset:44288
	ds_read_b128 v[16:19], v50 offset:43008
	v_add_f32_dpp v48, v48, v48 row_mirror row_mask:0xf bank_mask:0xf bound_ctrl:1
	v_pk_fma_f32 v[94:95], v[32:33], v[48:49], v[94:95] op_sel_hi:[1,0,1]
	v_pk_fma_f32 v[96:97], v[34:35], v[48:49], v[96:97] op_sel_hi:[1,0,1]
	v_pk_mul_f32 v[48:49], v[94:95], v[0:1]
	v_pk_mul_f32 v[76:77], v[94:95], v[36:37]
	v_pk_fma_f32 v[48:49], v[96:97], v[2:3], v[48:49]
	v_pk_fma_f32 v[76:77], v[96:97], v[38:39], v[76:77]
	v_add_f32_e32 v48, v48, v49
	v_add_f32_e32 v71, v76, v77
	ds_read_b128 v[0:3], v50 offset:47104
	ds_read_b128 v[28:31], v50 offset:45056
	ds_read_b128 v[24:27], v50 offset:44800
	s_waitcnt lgkmcnt(3)
	v_add_f32_dpp v48, v48, v48 quad_perm:[1,0,3,2] row_mask:0xf bank_mask:0xf bound_ctrl:1
	v_pk_mul_f32 v[44:45], v[8:9], v[40:41] op_sel_hi:[1,0]
	v_pk_mul_f32 v[46:47], v[10:11], v[40:41] op_sel_hi:[1,0]
	v_add_f32_dpp v48, v48, v48 quad_perm:[2,3,0,1] row_mask:0xf bank_mask:0xf bound_ctrl:1
	v_pk_fma_f32 v[44:45], v[94:95], v[4:5], v[44:45]
	v_pk_fma_f32 v[46:47], v[96:97], v[6:7], v[46:47]
	v_add_f32_dpp v48, v48, v48 row_half_mirror row_mask:0xf bank_mask:0xf bound_ctrl:1
	ds_read_b128 v[32:35], v50 offset:45824
	ds_read_b128 v[36:39], v50 offset:44544
	v_add_f32_dpp v48, v48, v48 row_mirror row_mask:0xf bank_mask:0xf bound_ctrl:1
	v_pk_fma_f32 v[44:45], v[12:13], v[48:49], v[44:45] op_sel_hi:[1,0,1]
	v_pk_fma_f32 v[46:47], v[14:15], v[48:49], v[46:47] op_sel_hi:[1,0,1]
	v_pk_mul_f32 v[48:49], v[44:45], v[20:21]
	v_pk_mul_f32 v[76:77], v[44:45], v[16:17]
	v_pk_fma_f32 v[48:49], v[46:47], v[22:23], v[48:49]
	v_pk_fma_f32 v[76:77], v[46:47], v[18:19], v[76:77]
	v_add_f32_e32 v48, v48, v49
	v_add_f32_e32 v72, v76, v77
	ds_read_b128 v[20:23], v50 offset:48640
	ds_read_b128 v[8:11], v50 offset:46592
	ds_read2st64_b32 v[42:43], v51 offset0:183 offset1:189
	ds_read_b128 v[4:7], v50 offset:46336
	s_waitcnt lgkmcnt(4)
	v_add_f32_dpp v48, v48, v48 quad_perm:[1,0,3,2] row_mask:0xf bank_mask:0xf bound_ctrl:1
	v_pk_mul_f32 v[94:95], v[28:29], v[40:41] op_sel:[0,1]
	v_pk_mul_f32 v[96:97], v[30:31], v[40:41] op_sel:[0,1]
	v_add_f32_dpp v48, v48, v48 quad_perm:[2,3,0,1] row_mask:0xf bank_mask:0xf bound_ctrl:1
	v_pk_fma_f32 v[94:95], v[44:45], v[24:25], v[94:95]
	v_pk_fma_f32 v[96:97], v[46:47], v[26:27], v[96:97]
	v_add_f32_dpp v48, v48, v48 row_half_mirror row_mask:0xf bank_mask:0xf bound_ctrl:1
	ds_read_b128 v[12:15], v50 offset:47360
	ds_read_b128 v[16:19], v50 offset:46080
	v_add_f32_dpp v48, v48, v48 row_mirror row_mask:0xf bank_mask:0xf bound_ctrl:1
	v_pk_fma_f32 v[94:95], v[32:33], v[48:49], v[94:95] op_sel_hi:[1,0,1]
	v_pk_fma_f32 v[96:97], v[34:35], v[48:49], v[96:97] op_sel_hi:[1,0,1]
	v_pk_mul_f32 v[48:49], v[94:95], v[0:1]
	v_pk_mul_f32 v[76:77], v[94:95], v[36:37]
	v_pk_fma_f32 v[48:49], v[96:97], v[2:3], v[48:49]
	v_pk_fma_f32 v[76:77], v[96:97], v[38:39], v[76:77]
	v_add_f32_e32 v48, v48, v49
	v_add_f32_e32 v73, v76, v77
	ds_read_b128 v[28:31], v50 offset:48128
	ds_read_b128 v[24:27], v50 offset:47872
	s_waitcnt lgkmcnt(2)
; __device__ __forceinline__ float sum16(float x) { x += dpp_f<0xB1>(x); x += dpp_f<0x4E>(x); x += dpp_f<0x141>(x); x += dpp_f<0x140>(x); return x; }
; __device__ __forceinline__ void rwkv_scan_phase(LAS unsigned char* lds, const bf16_t* RKV, const float* DEC, const float* AF, const float* k_k, const float* k_a, const float* r_k, float* BON, float* Y, int bx, const int tid) {
;     ...
;                 const f32x2 a01 = {a4[0], a4[1]}, a23 = {a4[2], a4[3]}, w01 = {w4[0], w4[1]}, w23 = {w4[2], w4[3]}, b01 = {b4[0], b4[1]}, b23 = {b4[2], b4[3]}, k01 = {k4[0], k4[1]}, k23 = {k4[2], k4[3]}, r01 = {r4[0], r4[1]}, r23 = {r4[2], r4[3]};
;                 const f32x2 tsa = S01 * a01 + S23 * a23; const float sa = sum16(tsa[0] + tsa[1]);
;                 S01 = S01 * w01 + (b01 * sa + k01 * vv); S23 = S23 * w23 + (b23 * sa + k23 * vv);
;                 const f32x2 ty = S01 * r01 + S23 * r23; const float y = sum16(ty[0] + ty[1]);
;                 ykeep = ((lane & 15) == (t & 15)) ? y : ykeep;
;                 if ((t & 15) == 15) yp[(size_t)(c * SC_T + (t - 15) + (lane & 15)) * 2048] = ykeep;
	v_add_f32_dpp v48, v48, v48 quad_perm:[1,0,3,2] row_mask:0xf bank_mask:0xf bound_ctrl:1
	v_pk_mul_f32 v[44:45], v[8:9], v[42:43] op_sel_hi:[1,0]
	v_pk_mul_f32 v[46:47], v[10:11], v[42:43] op_sel_hi:[1,0]
	v_add_f32_dpp v48, v48, v48 quad_perm:[2,3,0,1] row_mask:0xf bank_mask:0xf bound_ctrl:1
	v_pk_fma_f32 v[44:45], v[94:95], v[4:5], v[44:45]
	v_pk_fma_f32 v[46:47], v[96:97], v[6:7], v[46:47]
	v_add_f32_dpp v48, v48, v48 row_half_mirror row_mask:0xf bank_mask:0xf bound_ctrl:1
	ds_read_b128 v[32:35], v50 offset:48896
	ds_read_b128 v[36:39], v50 offset:47616
	v_add_f32_dpp v48, v48, v48 row_mirror row_mask:0xf bank_mask:0xf bound_ctrl:1
	v_pk_fma_f32 v[44:45], v[12:13], v[48:49], v[44:45] op_sel_hi:[1,0,1]
	v_pk_fma_f32 v[46:47], v[14:15], v[48:49], v[46:47] op_sel_hi:[1,0,1]
	v_pk_mul_f32 v[48:49], v[44:45], v[20:21]
	v_pk_mul_f32 v[76:77], v[44:45], v[16:17]
	v_pk_fma_f32 v[48:49], v[46:47], v[22:23], v[48:49]
	v_pk_fma_f32 v[76:77], v[46:47], v[18:19], v[76:77]
	v_add_f32_e32 v48, v48, v49
	v_add_f32_e32 v74, v76, v77
	s_waitcnt lgkmcnt(0)
	s_nop 0
	v_add_f32_dpp v48, v48, v48 quad_perm:[1,0,3,2] row_mask:0xf bank_mask:0xf bound_ctrl:1
	v_pk_mul_f32 v[94:95], v[28:29], v[42:43] op_sel:[0,1]
	v_pk_mul_f32 v[96:97], v[30:31], v[42:43] op_sel:[0,1]
	v_add_f32_dpp v48, v48, v48 quad_perm:[2,3,0,1] row_mask:0xf bank_mask:0xf bound_ctrl:1
	v_pk_fma_f32 v[94:95], v[44:45], v[24:25], v[94:95]
	v_pk_fma_f32 v[96:97], v[46:47], v[26:27], v[96:97]
	v_add_f32_dpp v48, v48, v48 row_half_mirror row_mask:0xf bank_mask:0xf bound_ctrl:1
	s_nop 1
	v_add_f32_dpp v48, v48, v48 row_mirror row_mask:0xf bank_mask:0xf bound_ctrl:1
	v_pk_fma_f32 v[94:95], v[32:33], v[48:49], v[94:95] op_sel_hi:[1,0,1]
	v_pk_fma_f32 v[96:97], v[34:35], v[48:49], v[96:97] op_sel_hi:[1,0,1]
	v_pk_mul_f32 v[76:77], v[94:95], v[36:37]
	v_pk_fma_f32 v[76:77], v[96:97], v[38:39], v[76:77]
	v_add_f32_e32 v75, v76, v77
	v_add_f32_dpp v60, v60, v60 row_mirror row_mask:0xf bank_mask:0x3 bound_ctrl:1
	v_add_f32_dpp v60, v68, v68 row_mirror row_mask:0xf bank_mask:0xc bound_ctrl:1
	v_add_f32_dpp v61, v61, v61 row_mirror row_mask:0xf bank_mask:0x3 bound_ctrl:1
	v_add_f32_dpp v61, v69, v69 row_mirror row_mask:0xf bank_mask:0xc bound_ctrl:1
	v_add_f32_dpp v62, v62, v62 row_mirror row_mask:0xf bank_mask:0x3 bound_ctrl:1
	v_add_f32_dpp v62, v70, v70 row_mirror row_mask:0xf bank_mask:0xc bound_ctrl:1
	v_add_f32_dpp v63, v63, v63 row_mirror row_mask:0xf bank_mask:0x3 bound_ctrl:1
	v_add_f32_dpp v63, v71, v71 row_mirror row_mask:0xf bank_mask:0xc bound_ctrl:1
	v_add_f32_dpp v64, v64, v64 row_mirror row_mask:0xf bank_mask:0x3 bound_ctrl:1
	v_add_f32_dpp v64, v72, v72 row_mirror row_mask:0xf bank_mask:0xc bound_ctrl:1
	v_add_f32_dpp v65, v65, v65 row_mirror row_mask:0xf bank_mask:0x3 bound_ctrl:1
	v_add_f32_dpp v65, v73, v73 row_mirror row_mask:0xf bank_mask:0xc bound_ctrl:1
	v_add_f32_dpp v66, v66, v66 row_mirror row_mask:0xf bank_mask:0x3 bound_ctrl:1
	v_add_f32_dpp v66, v74, v74 row_mirror row_mask:0xf bank_mask:0xc bound_ctrl:1
	v_add_f32_dpp v67, v67, v67 row_mirror row_mask:0xf bank_mask:0x3 bound_ctrl:1
	v_add_f32_dpp v67, v75, v75 row_mirror row_mask:0xf bank_mask:0xc bound_ctrl:1
	v_add_f32_dpp v60, v60, v60 row_half_mirror row_mask:0xf bank_mask:0x5 bound_ctrl:1
	v_add_f32_dpp v60, v64, v64 row_half_mirror row_mask:0xf bank_mask:0xa bound_ctrl:1
	v_add_f32_dpp v61, v61, v61 row_half_mirror row_mask:0xf bank_mask:0x5 bound_ctrl:1
	v_add_f32_dpp v61, v65, v65 row_half_mirror row_mask:0xf bank_mask:0xa bound_ctrl:1
	v_add_f32_dpp v62, v62, v62 row_half_mirror row_mask:0xf bank_mask:0x5 bound_ctrl:1
	v_add_f32_dpp v62, v66, v66 row_half_mirror row_mask:0xf bank_mask:0xa bound_ctrl:1
	v_add_f32_dpp v63, v63, v63 row_half_mirror row_mask:0xf bank_mask:0x5 bound_ctrl:1
	v_add_f32_dpp v63, v67, v67 row_half_mirror row_mask:0xf bank_mask:0xa bound_ctrl:1
	v_cndmask_b32_e64 v76, v62, v60, s[46:47]
	v_cndmask_b32_e64 v77, v63, v61, s[46:47]
	v_cndmask_b32_e64 v78, v60, v62, s[46:47]
	v_cndmask_b32_e64 v79, v61, v63, s[46:47]
	v_add_f32_dpp v60, v76, v78 quad_perm:[2,3,0,1] row_mask:0xf bank_mask:0xf bound_ctrl:1
	v_add_f32_dpp v61, v77, v79 quad_perm:[2,3,0,1] row_mask:0xf bank_mask:0xf bound_ctrl:1
	v_cndmask_b32_e64 v76, v61, v60, s[40:41]
	v_cndmask_b32_e64 v78, v60, v61, s[40:41]
	v_lshl_add_u64 v[52:53], v[92:93], 0, s[76:77]
	s_nop 0
	v_add_f32_dpp v60, v76, v78 quad_perm:[1,0,3,2] row_mask:0xf bank_mask:0xf bound_ctrl:1
	global_store_dword v[52:53], v60, off
	s_branch .LBB0_223

; __device__ __forceinline__ u32x4 pack8(f32x4 a, f32x4 b) { u32x4 w; w.x = cvt_pk_bf16(a[0], a[1]); w.y = cvt_pk_bf16(a[2], a[3]); w.z = cvt_pk_bf16(b[0], b[1]); w.w = cvt_pk_bf16(b[2], b[3]); return w; }
; #define EPI_END } asm volatile("" ::: "memory"); }
;     __device__ __forceinline__ void operator()(const f32x4 (&acc)[2][2][4][2], const pg8::Unit& u, int wr, int wc, int fr, int fq) const {
;     ...
;         if (mode == EM_RESID) {
;             EPI_BEGIN { const size_t off = (size_t)row * ldc + col; f32x4 r0 = *(const f32x4*)(res + off), r1 = *(const f32x4*)(res + off + 4);
;                 if (p0) { const f32x2 ms = *(const f32x2*)(f0 + 2 * (size_t)row); const f32x4 g0 = *(const f32x4*)(p0 + col), g1 = *(const f32x4*)(p0 + col + 4), b0 = *(const f32x4*)(p1 + col), b1 = *(const f32x4*)(p1 + col + 4);
;                     r0 = (r0 - ms[0]) * ms[1] * g0 + b0; r1 = (r1 - ms[0]) * ms[1] * g1 + b1; }
;                 if (bias) { v0 += *(const f32x4*)(bias + col); v1 += *(const f32x4*)(bias + col + 4); }
;                 *(f32x4*)(outf + off) = r0 * ALPHA + v0; *(f32x4*)(outf + off + 4) = r1 * ALPHA + v1; } EPI_END
;         } else if (mode == EM_RELU2) {
;             EPI_BEGIN { const f32x4 z = {0.f, 0.f, 0.f, 0.f}; v0 = __builtin_elementwise_max(v0, z); v1 = __builtin_elementwise_max(v1, z); v0 = v0 * v0; v1 = v1 * v1;
;                 *(u32x4*)(o0 + (size_t)row * ldc + col) = pack8(v0, v1); } EPI_END
.LBB0_1168:
	s_andn2_b64 vcc, exec, s[18:19]
	s_cbranch_vccnz .LBB0_1237
	v_ashrrev_i32_e32 v159, 31, v158
	v_or_b32_e32 v172, 16, v158
	v_or_b32_e32 v170, 32, v158
	v_or_b32_e32 v168, 48, v158
	v_add_u32_e32 v166, 0x80, v158
	s_mov_b64 s[18:19], -1
	s_cmp_gt_i32 s52, 0
	v_ashrrev_i32_e32 v157, 31, v156
	v_mul_lo_u32 v130, s59, v158
	s_waitcnt lgkmcnt(0)
	v_mul_lo_u32 v131, s58, v159
	v_mul_lo_u32 v171, s59, v172
	v_mul_lo_u32 v169, s59, v170
	v_mul_lo_u32 v155, s59, v168
	v_ashrrev_i32_e32 v167, 31, v166
	v_mul_lo_u32 v137, s59, v166
	v_add_u32_e32 v136, 0x90, v158
	s_cbranch_scc0 .LBB0_1171
	v_max_f32_e32 v129, 0, v125
	v_max_f32_e32 v128, 0, v124
	v_max_f32_e32 v133, 0, v127
	v_max_f32_e32 v132, 0, v126
	v_max_f32_e32 v135, 0, v121
	v_max_f32_e32 v161, 0, v123
	v_pk_mul_f32 v[128:129], v[128:129], v[128:129]
	v_max_f32_e32 v134, 0, v120
	v_max_f32_e32 v160, 0, v122
	v_pk_mul_f32 v[162:163], v[132:133], v[132:133]
	v_cvt_pk_bf16_f32 v132, v128, v129
	v_mad_u64_u32 v[128:129], s[18:19], s58, v158, 0
	v_pk_mul_f32 v[160:161], v[160:161], v[160:161]
	v_pk_mul_f32 v[134:135], v[134:135], v[134:135]
	v_add3_u32 v129, v129, v131, v130
	v_cvt_pk_bf16_f32 v133, v162, v163
	v_cvt_pk_bf16_f32 v134, v134, v135
	v_cvt_pk_bf16_f32 v135, v160, v161
	v_lshl_add_u64 v[160:161], v[128:129], 1, s[94:95]
	v_lshlrev_b64 v[128:129], 1, v[156:157]
	v_lshl_add_u64 v[160:161], v[160:161], 0, v[128:129]
	global_store_dwordx4 v[160:161], v[132:135], off
	s_nop 1
	v_max_f32_e32 v163, 0, v113
	v_max_f32_e32 v133, 0, v117
	v_max_f32_e32 v135, 0, v119
	v_max_f32_e32 v132, 0, v116
	v_max_f32_e32 v134, 0, v118
	v_max_f32_e32 v162, 0, v112
	v_max_f32_e32 v165, 0, v115
	v_pk_mul_f32 v[134:135], v[134:135], v[134:135]
	v_pk_mul_f32 v[132:133], v[132:133], v[132:133]
	v_max_f32_e32 v164, 0, v114
	v_pk_mul_f32 v[162:163], v[162:163], v[162:163]
	v_cvt_pk_bf16_f32 v132, v132, v133
	v_cvt_pk_bf16_f32 v133, v134, v135
	v_pk_mul_f32 v[164:165], v[164:165], v[164:165]
	v_cvt_pk_bf16_f32 v134, v162, v163
	v_cvt_pk_bf16_f32 v135, v164, v165
	global_store_dwordx4 v[160:161], v[132:135], off offset:256
	s_nop 1
	v_max_f32_e32 v161, 0, v105
	v_max_f32_e32 v133, 0, v109
	v_max_f32_e32 v135, 0, v111
	v_max_f32_e32 v132, 0, v108
	v_max_f32_e32 v134, 0, v110
	v_max_f32_e32 v160, 0, v104
	v_pk_mul_f32 v[134:135], v[134:135], v[134:135]
	v_pk_mul_f32 v[132:133], v[132:133], v[132:133]
	v_pk_mul_f32 v[160:161], v[160:161], v[160:161]
	v_cvt_pk_bf16_f32 v132, v132, v133
	v_cvt_pk_bf16_f32 v133, v134, v135
	v_max_f32_e32 v163, 0, v107
	v_cvt_pk_bf16_f32 v134, v160, v161
	v_mad_u64_u32 v[160:161], s[18:19], s58, v172, 0
	v_add3_u32 v161, v161, v131, v171
	v_lshl_add_u64 v[160:161], v[160:161], 1, s[94:95]
	v_max_f32_e32 v162, 0, v106
	v_lshl_add_u64 v[160:161], v[160:161], 0, v[128:129]
	v_pk_mul_f32 v[162:163], v[162:163], v[162:163]
	v_cvt_pk_bf16_f32 v135, v162, v163
	global_store_dwordx4 v[160:161], v[132:135], off
	s_nop 1
	v_max_f32_e32 v163, 0, v97
	v_max_f32_e32 v133, 0, v101
	v_max_f32_e32 v135, 0, v103
	v_max_f32_e32 v132, 0, v100
	v_max_f32_e32 v134, 0, v102
	v_max_f32_e32 v162, 0, v96
	v_max_f32_e32 v165, 0, v99
	v_pk_mul_f32 v[134:135], v[134:135], v[134:135]
	v_pk_mul_f32 v[132:133], v[132:133], v[132:133]
	v_max_f32_e32 v164, 0, v98
	v_pk_mul_f32 v[162:163], v[162:163], v[162:163]
	v_cvt_pk_bf16_f32 v132, v132, v133
	v_cvt_pk_bf16_f32 v133, v134, v135
	v_pk_mul_f32 v[164:165], v[164:165], v[164:165]
	v_cvt_pk_bf16_f32 v134, v162, v163
	v_cvt_pk_bf16_f32 v135, v164, v165
	global_store_dwordx4 v[160:161], v[132:135], off offset:256
	s_nop 1
	v_max_f32_e32 v161, 0, v89
	v_max_f32_e32 v133, 0, v93
	v_max_f32_e32 v135, 0, v95
	v_max_f32_e32 v132, 0, v92
	v_max_f32_e32 v134, 0, v94
	v_max_f32_e32 v160, 0, v88
	v_pk_mul_f32 v[134:135], v[134:135], v[134:135]
	v_pk_mul_f32 v[132:133], v[132:133], v[132:133]
	v_pk_mul_f32 v[160:161], v[160:161], v[160:161]
	v_cvt_pk_bf16_f32 v132, v132, v133
	v_cvt_pk_bf16_f32 v133, v134, v135
	v_max_f32_e32 v163, 0, v91
	v_cvt_pk_bf16_f32 v134, v160, v161
	v_mad_u64_u32 v[160:161], s[18:19], s58, v170, 0
	v_add3_u32 v161, v161, v131, v169
	v_lshl_add_u64 v[160:161], v[160:161], 1, s[94:95]
	v_max_f32_e32 v162, 0, v90
	v_lshl_add_u64 v[160:161], v[160:161], 0, v[128:129]
	v_pk_mul_f32 v[162:163], v[162:163], v[162:163]
	v_cvt_pk_bf16_f32 v135, v162, v163
	global_store_dwordx4 v[160:161], v[132:135], off
	s_nop 1
	v_max_f32_e32 v163, 0, v81
	v_max_f32_e32 v133, 0, v85
	v_max_f32_e32 v135, 0, v87
	v_max_f32_e32 v132, 0, v84
	v_max_f32_e32 v134, 0, v86
	v_max_f32_e32 v162, 0, v80
	v_max_f32_e32 v165, 0, v83
	v_pk_mul_f32 v[134:135], v[134:135], v[134:135]
	v_pk_mul_f32 v[132:133], v[132:133], v[132:133]
	v_max_f32_e32 v164, 0, v82
	v_pk_mul_f32 v[162:163], v[162:163], v[162:163]
	v_cvt_pk_bf16_f32 v132, v132, v133
	v_cvt_pk_bf16_f32 v133, v134, v135
	v_pk_mul_f32 v[164:165], v[164:165], v[164:165]
	v_cvt_pk_bf16_f32 v134, v162, v163
	v_cvt_pk_bf16_f32 v135, v164, v165
	global_store_dwordx4 v[160:161], v[132:135], off offset:256
	s_nop 1
	v_max_f32_e32 v161, 0, v73
	v_max_f32_e32 v133, 0, v77
	v_max_f32_e32 v135, 0, v79
	v_max_f32_e32 v132, 0, v76
	v_max_f32_e32 v134, 0, v78
	v_max_f32_e32 v160, 0, v72
	v_pk_mul_f32 v[134:135], v[134:135], v[134:135]
	v_pk_mul_f32 v[132:133], v[132:133], v[132:133]
	v_pk_mul_f32 v[160:161], v[160:161], v[160:161]
	v_cvt_pk_bf16_f32 v132, v132, v133
	v_cvt_pk_bf16_f32 v133, v134, v135
	v_max_f32_e32 v163, 0, v75
	v_cvt_pk_bf16_f32 v134, v160, v161
	v_mad_u64_u32 v[160:161], s[18:19], s58, v168, 0
	v_add3_u32 v161, v161, v131, v155
	v_lshl_add_u64 v[160:161], v[160:161], 1, s[94:95]
	v_max_f32_e32 v162, 0, v74
; __device__ __forceinline__ u32x4 pack8(f32x4 a, f32x4 b) { u32x4 w; w.x = cvt_pk_bf16(a[0], a[1]); w.y = cvt_pk_bf16(a[2], a[3]); w.z = cvt_pk_bf16(b[0], b[1]); w.w = cvt_pk_bf16(b[2], b[3]); return w; }
; #define EPI_END } asm volatile("" ::: "memory"); }
;     __device__ __forceinline__ void operator()(const f32x4 (&acc)[2][2][4][2], const pg8::Unit& u, int wr, int wc, int fr, int fq) const {
;     ...
;         if (mode == EM_RESID) {
;             EPI_BEGIN { const size_t off = (size_t)row * ldc + col; f32x4 r0 = *(const f32x4*)(res + off), r1 = *(const f32x4*)(res + off + 4);
;                 if (p0) { const f32x2 ms = *(const f32x2*)(f0 + 2 * (size_t)row); const f32x4 g0 = *(const f32x4*)(p0 + col), g1 = *(const f32x4*)(p0 + col + 4), b0 = *(const f32x4*)(p1 + col), b1 = *(const f32x4*)(p1 + col + 4);
;                     r0 = (r0 - ms[0]) * ms[1] * g0 + b0; r1 = (r1 - ms[0]) * ms[1] * g1 + b1; }
;                 if (bias) { v0 += *(const f32x4*)(bias + col); v1 += *(const f32x4*)(bias + col + 4); }
;                 *(f32x4*)(outf + off) = r0 * ALPHA + v0; *(f32x4*)(outf + off + 4) = r1 * ALPHA + v1; } EPI_END
;         } else if (mode == EM_RELU2) {
;             EPI_BEGIN { const f32x4 z = {0.f, 0.f, 0.f, 0.f}; v0 = __builtin_elementwise_max(v0, z); v1 = __builtin_elementwise_max(v1, z); v0 = v0 * v0; v1 = v1 * v1;
;                 *(u32x4*)(o0 + (size_t)row * ldc + col) = pack8(v0, v1); } EPI_END
	v_lshl_add_u64 v[160:161], v[160:161], 0, v[128:129]
	v_pk_mul_f32 v[162:163], v[162:163], v[162:163]
	v_cvt_pk_bf16_f32 v135, v162, v163
	global_store_dwordx4 v[160:161], v[132:135], off
	s_nop 1
	v_max_f32_e32 v163, 0, v65
	v_max_f32_e32 v133, 0, v69
	v_max_f32_e32 v135, 0, v71
	v_max_f32_e32 v132, 0, v68
	v_max_f32_e32 v134, 0, v70
	v_max_f32_e32 v162, 0, v64
	v_max_f32_e32 v165, 0, v67
	v_pk_mul_f32 v[134:135], v[134:135], v[134:135]
	v_pk_mul_f32 v[132:133], v[132:133], v[132:133]
	v_max_f32_e32 v164, 0, v66
	v_pk_mul_f32 v[162:163], v[162:163], v[162:163]
	v_cvt_pk_bf16_f32 v132, v132, v133
	v_cvt_pk_bf16_f32 v133, v134, v135
	v_pk_mul_f32 v[164:165], v[164:165], v[164:165]
	v_cvt_pk_bf16_f32 v134, v162, v163
	v_cvt_pk_bf16_f32 v135, v164, v165
	global_store_dwordx4 v[160:161], v[132:135], off offset:256
	s_nop 1
	v_max_f32_e32 v161, 0, v57
	v_max_f32_e32 v133, 0, v61
	v_max_f32_e32 v135, 0, v63
	v_max_f32_e32 v163, 0, v59
	v_max_f32_e32 v132, 0, v60
	v_max_f32_e32 v134, 0, v62
	v_max_f32_e32 v160, 0, v56
	v_max_f32_e32 v162, 0, v58
	v_pk_mul_f32 v[134:135], v[134:135], v[134:135]
	v_pk_mul_f32 v[132:133], v[132:133], v[132:133]
	v_pk_mul_f32 v[162:163], v[162:163], v[162:163]
	v_pk_mul_f32 v[160:161], v[160:161], v[160:161]
	v_cvt_pk_bf16_f32 v132, v132, v133
	v_cvt_pk_bf16_f32 v133, v134, v135
	v_cvt_pk_bf16_f32 v134, v160, v161
	v_cvt_pk_bf16_f32 v135, v162, v163
	v_mul_lo_u32 v162, s58, v167
	v_mad_u64_u32 v[160:161], s[18:19], s58, v166, 0
	v_add3_u32 v161, v161, v162, v137
	v_lshl_add_u64 v[160:161], v[160:161], 1, s[94:95]
	v_lshl_add_u64 v[160:161], v[160:161], 0, v[128:129]
	global_store_dwordx4 v[160:161], v[132:135], off
	s_nop 1
	v_max_f32_e32 v163, 0, v49
	v_max_f32_e32 v133, 0, v53
	v_max_f32_e32 v135, 0, v55
	v_max_f32_e32 v132, 0, v52
	v_max_f32_e32 v134, 0, v54
	v_max_f32_e32 v162, 0, v48
	v_max_f32_e32 v165, 0, v51
	v_pk_mul_f32 v[134:135], v[134:135], v[134:135]
	v_pk_mul_f32 v[132:133], v[132:133], v[132:133]
	v_max_f32_e32 v164, 0, v50
	v_pk_mul_f32 v[162:163], v[162:163], v[162:163]
	v_cvt_pk_bf16_f32 v132, v132, v133
	v_cvt_pk_bf16_f32 v133, v134, v135
	v_pk_mul_f32 v[164:165], v[164:165], v[164:165]
	v_cvt_pk_bf16_f32 v134, v162, v163
	v_cvt_pk_bf16_f32 v135, v164, v165
	global_store_dwordx4 v[160:161], v[132:135], off offset:256
	s_nop 1
	v_max_f32_e32 v161, 0, v41
	v_max_f32_e32 v133, 0, v45
	v_max_f32_e32 v135, 0, v47
	v_max_f32_e32 v163, 0, v43
	v_max_f32_e32 v132, 0, v44
	v_max_f32_e32 v134, 0, v46
	v_max_f32_e32 v160, 0, v40
	v_max_f32_e32 v162, 0, v42
	v_ashrrev_i32_e32 v164, 31, v136
	v_pk_mul_f32 v[134:135], v[134:135], v[134:135]
	v_pk_mul_f32 v[132:133], v[132:133], v[132:133]
	v_pk_mul_f32 v[162:163], v[162:163], v[162:163]
	v_pk_mul_f32 v[160:161], v[160:161], v[160:161]
	v_cvt_pk_bf16_f32 v132, v132, v133
	v_cvt_pk_bf16_f32 v133, v134, v135
	s_nop 0
	v_cvt_pk_bf16_f32 v134, v160, v161
	v_cvt_pk_bf16_f32 v135, v162, v163
	v_mul_lo_u32 v162, s58, v164
	v_mul_lo_u32 v163, s59, v136
	v_mad_u64_u32 v[160:161], s[18:19], s58, v136, 0
	v_add3_u32 v161, v161, v162, v163
	v_lshl_add_u64 v[160:161], v[160:161], 1, s[94:95]
	v_lshl_add_u64 v[160:161], v[160:161], 0, v[128:129]
	global_store_dwordx4 v[160:161], v[132:135], off
	s_nop 1
	v_max_f32_e32 v163, 0, v33
	v_max_f32_e32 v133, 0, v37
	v_max_f32_e32 v135, 0, v39
	v_max_f32_e32 v132, 0, v36
	v_max_f32_e32 v134, 0, v38
	v_max_f32_e32 v162, 0, v32
	v_max_f32_e32 v165, 0, v35
	v_pk_mul_f32 v[134:135], v[134:135], v[134:135]
	v_pk_mul_f32 v[132:133], v[132:133], v[132:133]
	v_max_f32_e32 v164, 0, v34
	v_pk_mul_f32 v[162:163], v[162:163], v[162:163]
	v_cvt_pk_bf16_f32 v132, v132, v133
	v_cvt_pk_bf16_f32 v133, v134, v135
	v_pk_mul_f32 v[164:165], v[164:165], v[164:165]
	v_cvt_pk_bf16_f32 v134, v162, v163
	v_cvt_pk_bf16_f32 v135, v164, v165
	global_store_dwordx4 v[160:161], v[132:135], off offset:256
	s_nop 1
	v_max_f32_e32 v161, 0, v25
	v_max_f32_e32 v133, 0, v29
	v_max_f32_e32 v135, 0, v31
	v_max_f32_e32 v163, 0, v27
	v_add_u32_e32 v164, 0xa0, v158
	v_max_f32_e32 v132, 0, v28
	v_max_f32_e32 v134, 0, v30
	v_max_f32_e32 v160, 0, v24
	v_max_f32_e32 v162, 0, v26
	v_ashrrev_i32_e32 v165, 31, v164
	v_pk_mul_f32 v[134:135], v[134:135], v[134:135]
	v_pk_mul_f32 v[132:133], v[132:133], v[132:133]
	v_pk_mul_f32 v[162:163], v[162:163], v[162:163]
	v_pk_mul_f32 v[160:161], v[160:161], v[160:161]
	v_cvt_pk_bf16_f32 v132, v132, v133
	v_cvt_pk_bf16_f32 v133, v134, v135
	s_nop 0
	v_cvt_pk_bf16_f32 v134, v160, v161
	v_cvt_pk_bf16_f32 v135, v162, v163
	v_mul_lo_u32 v162, s58, v165
	v_mul_lo_u32 v163, s59, v164
	v_mad_u64_u32 v[160:161], s[18:19], s58, v164, 0
	v_add3_u32 v161, v161, v162, v163
	v_lshl_add_u64 v[160:161], v[160:161], 1, s[94:95]
	v_lshl_add_u64 v[160:161], v[160:161], 0, v[128:129]
	global_store_dwordx4 v[160:161], v[132:135], off
	s_nop 1
	v_max_f32_e32 v163, 0, v17
	v_max_f32_e32 v133, 0, v21
	v_max_f32_e32 v135, 0, v23
	v_max_f32_e32 v132, 0, v20
	v_max_f32_e32 v134, 0, v22
	v_max_f32_e32 v162, 0, v16
	v_max_f32_e32 v165, 0, v19
	v_pk_mul_f32 v[134:135], v[134:135], v[134:135]
	v_pk_mul_f32 v[132:133], v[132:133], v[132:133]
	v_max_f32_e32 v164, 0, v18
	v_pk_mul_f32 v[162:163], v[162:163], v[162:163]
	v_cvt_pk_bf16_f32 v132, v132, v133
	v_cvt_pk_bf16_f32 v133, v134, v135
	v_pk_mul_f32 v[164:165], v[164:165], v[164:165]
	v_cvt_pk_bf16_f32 v134, v162, v163
	v_cvt_pk_bf16_f32 v135, v164, v165
	global_store_dwordx4 v[160:161], v[132:135], off offset:256
	s_nop 1
	v_max_f32_e32 v161, 0, v9
	v_max_f32_e32 v133, 0, v13
	v_max_f32_e32 v135, 0, v15
	v_max_f32_e32 v163, 0, v11
	v_add_u32_e32 v164, 0xb0, v158
	v_max_f32_e32 v132, 0, v12
	v_max_f32_e32 v134, 0, v14
	v_max_f32_e32 v160, 0, v8
	v_max_f32_e32 v162, 0, v10
	v_ashrrev_i32_e32 v165, 31, v164
	v_pk_mul_f32 v[134:135], v[134:135], v[134:135]
	v_pk_mul_f32 v[132:133], v[132:133], v[132:133]
	v_pk_mul_f32 v[162:163], v[162:163], v[162:163]
	v_pk_mul_f32 v[160:161], v[160:161], v[160:161]
	v_cvt_pk_bf16_f32 v132, v132, v133
	v_cvt_pk_bf16_f32 v133, v134, v135
	s_nop 0
	v_cvt_pk_bf16_f32 v134, v160, v161
	v_cvt_pk_bf16_f32 v135, v162, v163
	v_mul_lo_u32 v162, s58, v165
	v_mul_lo_u32 v163, s59, v164
	v_mad_u64_u32 v[160:161], s[18:19], s58, v164, 0
	v_add3_u32 v161, v161, v162, v163
	v_lshl_add_u64 v[160:161], v[160:161], 1, s[94:95]
	v_lshl_add_u64 v[128:129], v[160:161], 0, v[128:129]
	global_store_dwordx4 v[128:129], v[132:135], off
	s_nop 1
	v_max_f32_e32 v133, 0, v5
	v_max_f32_e32 v135, 0, v7
	v_max_f32_e32 v132, 0, v4
	v_max_f32_e32 v134, 0, v6
	v_max_f32_e32 v161, 0, v1
	v_max_f32_e32 v163, 0, v3
	v_max_f32_e32 v160, 0, v0
	v_max_f32_e32 v162, 0, v2
	v_pk_mul_f32 v[134:135], v[134:135], v[134:135]
	v_pk_mul_f32 v[132:133], v[132:133], v[132:133]
	v_pk_mul_f32 v[162:163], v[162:163], v[162:163]
	v_pk_mul_f32 v[160:161], v[160:161], v[160:161]
	v_cvt_pk_bf16_f32 v132, v132, v133
	v_cvt_pk_bf16_f32 v133, v134, v135
	s_mov_b64 s[18:19], 0
	v_cvt_pk_bf16_f32 v134, v160, v161
	v_cvt_pk_bf16_f32 v135, v162, v163
	global_store_dwordx4 v[128:129], v[132:135], off offset:256
	s_nop 1
